# main GEMM K-loops: MFMA order groups the four MFMAs that share an A fragment (B0/B1 macros merged), snake across m
# baseline (speedup 1.0000x reference)
.LBB0_255:
	s_ashr_i32 s15, s14, 31
	s_lshl_b64 s[20:21], s[14:15], 19
	s_add_u32 s42, s31, s20
	s_addc_u32 s43, s34, s21
	s_and_b64 s[20:21], s[4:5], exec
	s_cselect_b32 s15, s43, s53
	s_cselect_b32 s20, s42, s52
	s_ashr_i32 s13, s12, 31
	s_lshl_b64 s[50:51], s[12:13], 19
	s_add_u32 s50, s35, s50
	s_addc_u32 s51, s36, s51
	s_and_b64 s[58:59], s[4:5], exec
	s_cselect_b32 s13, s51, s57
	s_cselect_b32 s21, s50, s56
	s_add_u32 s52, s52, 0x40080
	s_addc_u32 s53, s53, 0
	s_add_u32 s73, s56, 0x100
	s_addc_u32 s75, s57, 0
	s_mov_b32 s82, -2
	s_add_u32 s0, s52, 0xfffc0080
	s_addc_u32 s56, s53, -1
	s_add_i32 s83, 0, 0x10000
	s_cmp_eq_u32 s82, 12
	s_cselect_b32 s59, s15, s56
	s_cselect_b32 s58, s20, s0
	s_cselect_b32 s57, s13, s75
	s_cselect_b32 s56, s21, s73
	s_add_i32 s0, 0, 0x14000
	v_add_u32_e32 v94, s83, v171
	v_add_u32_e32 v155, s0, v171
	ds_read_b128 v[74:77], v94
	ds_read_b128 v[78:81], v94 offset:1024
	ds_read_b128 v[90:93], v94 offset:2048
	ds_read_b128 v[94:97], v94 offset:3072
	ds_read_b128 v[180:183], v155
	ds_read_b128 v[184:187], v155 offset:1024
	ds_read_b128 v[188:191], v155 offset:2048
	ds_read_b128 v[192:195], v155 offset:3072
	v_lshl_add_u64 v[168:169], s[52:53], 0, v[164:165]
	s_add_i32 m0, s61, 0xc000
	ds_read_b128 v[196:199], v177
	ds_read_b128 v[200:203], v177 offset:1024
	ds_read_b128 v[204:207], v177 offset:2048
	ds_read_b128 v[208:211], v177 offset:3072
	ds_read_b128 v[212:215], v177 offset:4096
	ds_read_b128 v[216:219], v177 offset:5120
	ds_read_b128 v[230:233], v177 offset:6144
	ds_read_b128 v[238:241], v177 offset:7168
	global_load_lds_dwordx4 v[168:169], off
	v_lshl_add_u64 v[168:169], s[52:53], 0, v[166:167]
	s_add_i32 m0, s61, 0xe000
	s_nop 0
	global_load_lds_dwordx4 v[168:169], off
	s_waitcnt vmcnt(8)
	s_waitcnt lgkmcnt(0)
	s_barrier
	s_setprio 1
	s_waitcnt lgkmcnt(0)
	v_mfma_f32_16x16x32_bf16 v[142:145], v[74:77], v[196:199], 0
	v_mfma_f32_16x16x32_bf16 v[134:137], v[90:93], v[196:199], 0
	v_mfma_f32_16x16x32_bf16 v[138:141], v[180:183], v[196:199], 0
	v_mfma_f32_16x16x32_bf16 v[130:133], v[188:191], v[196:199], 0
	v_mfma_f32_16x16x32_bf16 v[114:117], v[188:191], v[204:207], 0
	v_mfma_f32_16x16x32_bf16 v[122:125], v[180:183], v[204:207], 0
	v_mfma_f32_16x16x32_bf16 v[118:121], v[90:93], v[204:207], 0
	v_mfma_f32_16x16x32_bf16 v[126:129], v[74:77], v[204:207], 0
	v_mfma_f32_16x16x32_bf16 v[110:113], v[74:77], v[212:215], 0
	v_mfma_f32_16x16x32_bf16 v[102:105], v[90:93], v[212:215], 0
	v_mfma_f32_16x16x32_bf16 v[106:109], v[180:183], v[212:215], 0
	v_mfma_f32_16x16x32_bf16 v[98:101], v[188:191], v[212:215], 0
	v_mfma_f32_16x16x32_bf16 v[66:69], v[188:191], v[230:233], 0
	v_mfma_f32_16x16x32_bf16 v[82:85], v[180:183], v[230:233], 0
	v_mfma_f32_16x16x32_bf16 v[70:73], v[90:93], v[230:233], 0
	v_mfma_f32_16x16x32_bf16 v[86:89], v[74:77], v[230:233], 0
	s_setprio 0
	s_setprio 1
	v_mfma_f32_16x16x32_bf16 v[142:145], v[78:81], v[200:203], v[142:145]
	v_mfma_f32_16x16x32_bf16 v[134:137], v[94:97], v[200:203], v[134:137]
	v_mfma_f32_16x16x32_bf16 v[138:141], v[184:187], v[200:203], v[138:141]
	v_mfma_f32_16x16x32_bf16 v[130:133], v[192:195], v[200:203], v[130:133]
	v_mfma_f32_16x16x32_bf16 v[114:117], v[192:195], v[208:211], v[114:117]
	v_mfma_f32_16x16x32_bf16 v[122:125], v[184:187], v[208:211], v[122:125]
	v_mfma_f32_16x16x32_bf16 v[118:121], v[94:97], v[208:211], v[118:121]
	v_mfma_f32_16x16x32_bf16 v[126:129], v[78:81], v[208:211], v[126:129]
	v_mfma_f32_16x16x32_bf16 v[110:113], v[78:81], v[216:219], v[110:113]
	v_mfma_f32_16x16x32_bf16 v[102:105], v[94:97], v[216:219], v[102:105]
	v_mfma_f32_16x16x32_bf16 v[106:109], v[184:187], v[216:219], v[106:109]
	v_mfma_f32_16x16x32_bf16 v[98:101], v[192:195], v[216:219], v[98:101]
	v_mfma_f32_16x16x32_bf16 v[66:69], v[192:195], v[238:241], v[66:69]
	v_mfma_f32_16x16x32_bf16 v[82:85], v[184:187], v[238:241], v[82:85]
	v_mfma_f32_16x16x32_bf16 v[70:73], v[94:97], v[238:241], v[70:73]
	v_mfma_f32_16x16x32_bf16 v[86:89], v[78:81], v[238:241], v[86:89]
	s_setprio 0
	s_barrier
	s_add_i32 s83, s83, s37
	v_lshl_add_u64 v[168:169], s[56:57], 0, v[150:151]
	s_mov_b32 m0, s83
	ds_read_b128 v[196:199], v177 offset:16384
	ds_read_b128 v[200:203], v177 offset:17408
	ds_read_b128 v[204:207], v177 offset:18432
	ds_read_b128 v[208:211], v177 offset:19456
	ds_read_b128 v[212:215], v177 offset:20480
	ds_read_b128 v[216:219], v177 offset:21504
	ds_read_b128 v[230:233], v177 offset:22528
	ds_read_b128 v[238:241], v177 offset:23552
	global_load_lds_dwordx4 v[168:169], off
	s_add_i32 m0, s83, 0x2000
	s_add_u32 s84, s56, 0x40000
	v_lshl_add_u64 v[242:243], s[56:57], 0, v[146:147]
	s_addc_u32 s85, s57, 0
	s_add_i32 s0, s0, s37
	global_load_lds_dwordx4 v[242:243], off
	v_lshl_add_u64 v[244:245], s[84:85], 0, v[150:151]
	s_mov_b32 m0, s0
	v_lshl_add_u64 v[246:247], s[58:59], 0, v[148:149]
	global_load_lds_dwordx4 v[244:245], off
	v_lshl_add_u64 v[244:245], s[84:85], 0, v[146:147]
	s_add_i32 m0, s0, 0x2000
	s_nop 0
	global_load_lds_dwordx4 v[244:245], off
	v_lshl_add_u64 v[244:245], s[58:59], 0, v[152:153]
	s_mov_b32 m0, s61
	s_nop 0
	global_load_lds_dwordx4 v[244:245], off
	s_mov_b32 m0, s64
	s_nop 0
	global_load_lds_dwordx4 v[246:247], off
	s_waitcnt vmcnt(8)
	s_waitcnt lgkmcnt(0)
	s_barrier
	s_setprio 1
	s_waitcnt lgkmcnt(0)
	v_mfma_f32_16x16x32_bf16 v[62:65], v[74:77], v[196:199], 0
	v_mfma_f32_16x16x32_bf16 v[54:57], v[90:93], v[196:199], 0
	v_mfma_f32_16x16x32_bf16 v[58:61], v[180:183], v[196:199], 0
	v_mfma_f32_16x16x32_bf16 v[50:53], v[188:191], v[196:199], 0
	v_mfma_f32_16x16x32_bf16 v[34:37], v[188:191], v[204:207], 0
	v_mfma_f32_16x16x32_bf16 v[42:45], v[180:183], v[204:207], 0
	v_mfma_f32_16x16x32_bf16 v[38:41], v[90:93], v[204:207], 0
	v_mfma_f32_16x16x32_bf16 v[46:49], v[74:77], v[204:207], 0
	v_mfma_f32_16x16x32_bf16 v[30:33], v[74:77], v[212:215], 0
	v_mfma_f32_16x16x32_bf16 v[22:25], v[90:93], v[212:215], 0
	v_mfma_f32_16x16x32_bf16 v[26:29], v[180:183], v[212:215], 0
	v_mfma_f32_16x16x32_bf16 v[18:21], v[188:191], v[212:215], 0
	v_mfma_f32_16x16x32_bf16 v[2:5], v[188:191], v[230:233], 0
	v_mfma_f32_16x16x32_bf16 v[10:13], v[180:183], v[230:233], 0
	v_mfma_f32_16x16x32_bf16 v[6:9], v[90:93], v[230:233], 0
	v_mfma_f32_16x16x32_bf16 v[14:17], v[74:77], v[230:233], 0
	s_setprio 0
	s_setprio 1
	v_mfma_f32_16x16x32_bf16 v[62:65], v[78:81], v[200:203], v[62:65]
	v_mfma_f32_16x16x32_bf16 v[54:57], v[94:97], v[200:203], v[54:57]
	v_mfma_f32_16x16x32_bf16 v[58:61], v[184:187], v[200:203], v[58:61]
	v_mfma_f32_16x16x32_bf16 v[50:53], v[192:195], v[200:203], v[50:53]
	v_mfma_f32_16x16x32_bf16 v[34:37], v[192:195], v[208:211], v[34:37]
	v_mfma_f32_16x16x32_bf16 v[42:45], v[184:187], v[208:211], v[42:45]
	v_mfma_f32_16x16x32_bf16 v[38:41], v[94:97], v[208:211], v[38:41]
	v_mfma_f32_16x16x32_bf16 v[46:49], v[78:81], v[208:211], v[46:49]
	v_mfma_f32_16x16x32_bf16 v[30:33], v[78:81], v[216:219], v[30:33]
	v_mfma_f32_16x16x32_bf16 v[22:25], v[94:97], v[216:219], v[22:25]
	v_mfma_f32_16x16x32_bf16 v[26:29], v[184:187], v[216:219], v[26:29]
	v_mfma_f32_16x16x32_bf16 v[18:21], v[192:195], v[216:219], v[18:21]
	v_mfma_f32_16x16x32_bf16 v[2:5], v[192:195], v[238:241], v[2:5]
	v_mfma_f32_16x16x32_bf16 v[10:13], v[184:187], v[238:241], v[10:13]
	v_mfma_f32_16x16x32_bf16 v[6:9], v[94:97], v[238:241], v[6:9]
	v_mfma_f32_16x16x32_bf16 v[14:17], v[78:81], v[238:241], v[14:17]
	s_setprio 0
	s_barrier
	s_add_i32 s0, 0, 0x18000
	s_add_i32 s83, 0, 0x1c000
	v_add_u32_e32 v94, s0, v171
	v_add_u32_e32 v155, s83, v171
	ds_read_b128 v[74:77], v94
	ds_read_b128 v[78:81], v94 offset:1024
	ds_read_b128 v[90:93], v94 offset:2048
	ds_read_b128 v[94:97], v94 offset:3072
	ds_read_b128 v[180:183], v155
	ds_read_b128 v[184:187], v155 offset:1024
	ds_read_b128 v[188:191], v155 offset:2048
	ds_read_b128 v[192:195], v155 offset:3072
	s_add_u32 s58, s58, 0x40000
	s_addc_u32 s59, s59, 0
	s_mov_b32 m0, s65
	v_lshl_add_u64 v[248:249], s[58:59], 0, v[152:153]
	ds_read_b128 v[196:199], v177 offset:32768
	ds_read_b128 v[200:203], v177 offset:33792
	ds_read_b128 v[204:207], v177 offset:34816
	ds_read_b128 v[208:211], v177 offset:35840
	ds_read_b128 v[212:215], v177 offset:36864
	ds_read_b128 v[216:219], v177 offset:37888
	ds_read_b128 v[230:233], v177 offset:38912
	ds_read_b128 v[238:241], v177 offset:39936
	global_load_lds_dwordx4 v[248:249], off
	v_lshl_add_u64 v[248:249], s[58:59], 0, v[148:149]
	s_mov_b32 m0, s66
	s_nop 0
	global_load_lds_dwordx4 v[248:249], off
	s_waitcnt vmcnt(8)
	s_waitcnt lgkmcnt(0)
	s_barrier
	s_setprio 1
	s_waitcnt lgkmcnt(0)
	v_mfma_f32_16x16x32_bf16 v[142:145], v[74:77], v[196:199], v[142:145]
	v_mfma_f32_16x16x32_bf16 v[134:137], v[90:93], v[196:199], v[134:137]
	v_mfma_f32_16x16x32_bf16 v[138:141], v[180:183], v[196:199], v[138:141]
	v_mfma_f32_16x16x32_bf16 v[130:133], v[188:191], v[196:199], v[130:133]
	v_mfma_f32_16x16x32_bf16 v[114:117], v[188:191], v[204:207], v[114:117]
	v_mfma_f32_16x16x32_bf16 v[122:125], v[180:183], v[204:207], v[122:125]
	v_mfma_f32_16x16x32_bf16 v[118:121], v[90:93], v[204:207], v[118:121]
	v_mfma_f32_16x16x32_bf16 v[126:129], v[74:77], v[204:207], v[126:129]
	v_mfma_f32_16x16x32_bf16 v[110:113], v[74:77], v[212:215], v[110:113]
	v_mfma_f32_16x16x32_bf16 v[102:105], v[90:93], v[212:215], v[102:105]
	v_mfma_f32_16x16x32_bf16 v[106:109], v[180:183], v[212:215], v[106:109]
	v_mfma_f32_16x16x32_bf16 v[98:101], v[188:191], v[212:215], v[98:101]
	v_mfma_f32_16x16x32_bf16 v[66:69], v[188:191], v[230:233], v[66:69]
	v_mfma_f32_16x16x32_bf16 v[82:85], v[180:183], v[230:233], v[82:85]
	v_mfma_f32_16x16x32_bf16 v[70:73], v[90:93], v[230:233], v[70:73]
	v_mfma_f32_16x16x32_bf16 v[86:89], v[74:77], v[230:233], v[86:89]
	s_setprio 0
	s_setprio 1
	v_mfma_f32_16x16x32_bf16 v[142:145], v[78:81], v[200:203], v[142:145]
	v_mfma_f32_16x16x32_bf16 v[134:137], v[94:97], v[200:203], v[134:137]
	v_mfma_f32_16x16x32_bf16 v[138:141], v[184:187], v[200:203], v[138:141]
	v_mfma_f32_16x16x32_bf16 v[130:133], v[192:195], v[200:203], v[130:133]
	v_mfma_f32_16x16x32_bf16 v[114:117], v[192:195], v[208:211], v[114:117]
	v_mfma_f32_16x16x32_bf16 v[122:125], v[184:187], v[208:211], v[122:125]
	v_mfma_f32_16x16x32_bf16 v[118:121], v[94:97], v[208:211], v[118:121]
	v_mfma_f32_16x16x32_bf16 v[126:129], v[78:81], v[208:211], v[126:129]
	v_mfma_f32_16x16x32_bf16 v[110:113], v[78:81], v[216:219], v[110:113]
	v_mfma_f32_16x16x32_bf16 v[102:105], v[94:97], v[216:219], v[102:105]
	v_mfma_f32_16x16x32_bf16 v[106:109], v[184:187], v[216:219], v[106:109]
	v_mfma_f32_16x16x32_bf16 v[98:101], v[192:195], v[216:219], v[98:101]
	v_mfma_f32_16x16x32_bf16 v[66:69], v[192:195], v[238:241], v[66:69]
	v_mfma_f32_16x16x32_bf16 v[82:85], v[184:187], v[238:241], v[82:85]
	v_mfma_f32_16x16x32_bf16 v[70:73], v[94:97], v[238:241], v[70:73]
	v_mfma_f32_16x16x32_bf16 v[86:89], v[78:81], v[238:241], v[86:89]
	s_setprio 0
	s_barrier
	s_add_i32 s0, s0, s37
	v_lshl_add_u64 v[168:169], v[168:169], 0, s[76:77]
	s_mov_b32 m0, s0
	ds_read_b128 v[196:199], v177 offset:49152
	ds_read_b128 v[200:203], v177 offset:50176
	ds_read_b128 v[204:207], v177 offset:51200
	ds_read_b128 v[208:211], v177 offset:52224
	ds_read_b128 v[212:215], v177 offset:53248
	ds_read_b128 v[216:219], v177 offset:54272
	ds_read_b128 v[230:233], v177 offset:55296
	ds_read_b128 v[238:241], v177 offset:56320
	global_load_lds_dwordx4 v[168:169], off
	s_add_i32 m0, s0, 0x2000
	s_add_u32 s56, s56, 0x40080
	v_lshl_add_u64 v[168:169], v[242:243], 0, s[76:77]
	s_addc_u32 s57, s57, 0
	s_add_i32 s0, s83, s37
	global_load_lds_dwordx4 v[168:169], off
	v_lshl_add_u64 v[168:169], s[56:57], 0, v[150:151]
	s_mov_b32 m0, s0
	s_nop 0
	global_load_lds_dwordx4 v[168:169], off
	v_lshl_add_u64 v[168:169], s[56:57], 0, v[146:147]
	s_add_i32 m0, s0, 0x2000
	s_nop 0
	global_load_lds_dwordx4 v[168:169], off
	v_lshl_add_u64 v[168:169], v[244:245], 0, s[76:77]
	s_mov_b32 m0, s67
	s_nop 0
	global_load_lds_dwordx4 v[168:169], off
	v_lshl_add_u64 v[168:169], v[246:247], 0, s[76:77]
	s_mov_b32 m0, s68
	s_nop 0
	global_load_lds_dwordx4 v[168:169], off
	s_waitcnt vmcnt(8)
	s_waitcnt lgkmcnt(0)
	s_barrier
	s_setprio 1
	s_waitcnt lgkmcnt(0)
	v_mfma_f32_16x16x32_bf16 v[62:65], v[74:77], v[196:199], v[62:65]
	v_mfma_f32_16x16x32_bf16 v[54:57], v[90:93], v[196:199], v[54:57]
	v_mfma_f32_16x16x32_bf16 v[58:61], v[180:183], v[196:199], v[58:61]
	v_mfma_f32_16x16x32_bf16 v[50:53], v[188:191], v[196:199], v[50:53]
	v_mfma_f32_16x16x32_bf16 v[34:37], v[188:191], v[204:207], v[34:37]
	v_mfma_f32_16x16x32_bf16 v[42:45], v[180:183], v[204:207], v[42:45]
	v_mfma_f32_16x16x32_bf16 v[38:41], v[90:93], v[204:207], v[38:41]
	v_mfma_f32_16x16x32_bf16 v[46:49], v[74:77], v[204:207], v[46:49]
	v_mfma_f32_16x16x32_bf16 v[30:33], v[74:77], v[212:215], v[30:33]
	v_mfma_f32_16x16x32_bf16 v[22:25], v[90:93], v[212:215], v[22:25]
	v_mfma_f32_16x16x32_bf16 v[26:29], v[180:183], v[212:215], v[26:29]
	v_mfma_f32_16x16x32_bf16 v[18:21], v[188:191], v[212:215], v[18:21]
	v_mfma_f32_16x16x32_bf16 v[2:5], v[188:191], v[230:233], v[2:5]
	v_mfma_f32_16x16x32_bf16 v[10:13], v[180:183], v[230:233], v[10:13]
	v_mfma_f32_16x16x32_bf16 v[6:9], v[90:93], v[230:233], v[6:9]
	v_mfma_f32_16x16x32_bf16 v[14:17], v[74:77], v[230:233], v[14:17]
	s_setprio 0
	s_setprio 1
	v_mfma_f32_16x16x32_bf16 v[62:65], v[78:81], v[200:203], v[62:65]
	v_mfma_f32_16x16x32_bf16 v[54:57], v[94:97], v[200:203], v[54:57]
	v_mfma_f32_16x16x32_bf16 v[58:61], v[184:187], v[200:203], v[58:61]
	v_mfma_f32_16x16x32_bf16 v[50:53], v[192:195], v[200:203], v[50:53]
	v_mfma_f32_16x16x32_bf16 v[34:37], v[192:195], v[208:211], v[34:37]
	v_mfma_f32_16x16x32_bf16 v[42:45], v[184:187], v[208:211], v[42:45]
	v_mfma_f32_16x16x32_bf16 v[38:41], v[94:97], v[208:211], v[38:41]
	v_mfma_f32_16x16x32_bf16 v[46:49], v[78:81], v[208:211], v[46:49]
	v_mfma_f32_16x16x32_bf16 v[30:33], v[78:81], v[216:219], v[30:33]
	v_mfma_f32_16x16x32_bf16 v[22:25], v[94:97], v[216:219], v[22:25]
	v_mfma_f32_16x16x32_bf16 v[26:29], v[184:187], v[216:219], v[26:29]
	v_mfma_f32_16x16x32_bf16 v[18:21], v[192:195], v[216:219], v[18:21]
	v_mfma_f32_16x16x32_bf16 v[2:5], v[192:195], v[238:241], v[2:5]
	v_mfma_f32_16x16x32_bf16 v[10:13], v[184:187], v[238:241], v[10:13]
	v_mfma_f32_16x16x32_bf16 v[6:9], v[94:97], v[238:241], v[6:9]
	v_mfma_f32_16x16x32_bf16 v[14:17], v[78:81], v[238:241], v[14:17]
	s_setprio 0
	s_barrier
	s_add_i32 s82, s82, 2
	s_add_u32 s52, s52, 0x100
	s_addc_u32 s53, s53, 0
	s_add_u32 s73, s73, 0x100
	s_addc_u32 s75, s75, 0
.LBB0_256:
	s_add_u32 s0, s52, 0xfffc0080
	s_addc_u32 s56, s53, -1
	s_add_i32 s83, 0, 0x10000
	s_cmp_eq_u32 s82, 12
	s_cselect_b32 s59, s15, s56
	s_cselect_b32 s58, s20, s0
	s_cselect_b32 s57, s13, s75
	s_cselect_b32 s56, s21, s73
	s_add_i32 s0, 0, 0x14000
	v_add_u32_e32 v94, s83, v171
	v_add_u32_e32 v155, s0, v171
	ds_read_b128 v[74:77], v94
	ds_read_b128 v[78:81], v94 offset:1024
	ds_read_b128 v[90:93], v94 offset:2048
	ds_read_b128 v[94:97], v94 offset:3072
	ds_read_b128 v[180:183], v155
	ds_read_b128 v[184:187], v155 offset:1024
	ds_read_b128 v[188:191], v155 offset:2048
	ds_read_b128 v[192:195], v155 offset:3072
	v_lshl_add_u64 v[168:169], s[52:53], 0, v[164:165]
	s_add_i32 m0, s61, 0xc000
	ds_read_b128 v[196:199], v177
	ds_read_b128 v[200:203], v177 offset:1024
	ds_read_b128 v[204:207], v177 offset:2048
	ds_read_b128 v[208:211], v177 offset:3072
	ds_read_b128 v[212:215], v177 offset:4096
	ds_read_b128 v[216:219], v177 offset:5120
	ds_read_b128 v[230:233], v177 offset:6144
	ds_read_b128 v[238:241], v177 offset:7168
	global_load_lds_dwordx4 v[168:169], off
	v_lshl_add_u64 v[168:169], s[52:53], 0, v[166:167]
	s_add_i32 m0, s61, 0xe000
	s_nop 0
	global_load_lds_dwordx4 v[168:169], off
	s_waitcnt vmcnt(8)
	s_waitcnt lgkmcnt(0)
	s_barrier
	s_setprio 1
	s_waitcnt lgkmcnt(0)
	v_mfma_f32_16x16x32_bf16 v[142:145], v[74:77], v[196:199], v[142:145]
	v_mfma_f32_16x16x32_bf16 v[134:137], v[90:93], v[196:199], v[134:137]
	v_mfma_f32_16x16x32_bf16 v[138:141], v[180:183], v[196:199], v[138:141]
	v_mfma_f32_16x16x32_bf16 v[130:133], v[188:191], v[196:199], v[130:133]
	v_mfma_f32_16x16x32_bf16 v[114:117], v[188:191], v[204:207], v[114:117]
	v_mfma_f32_16x16x32_bf16 v[122:125], v[180:183], v[204:207], v[122:125]
	v_mfma_f32_16x16x32_bf16 v[118:121], v[90:93], v[204:207], v[118:121]
	v_mfma_f32_16x16x32_bf16 v[126:129], v[74:77], v[204:207], v[126:129]
	v_mfma_f32_16x16x32_bf16 v[110:113], v[74:77], v[212:215], v[110:113]
	v_mfma_f32_16x16x32_bf16 v[102:105], v[90:93], v[212:215], v[102:105]
	v_mfma_f32_16x16x32_bf16 v[106:109], v[180:183], v[212:215], v[106:109]
	v_mfma_f32_16x16x32_bf16 v[98:101], v[188:191], v[212:215], v[98:101]
	v_mfma_f32_16x16x32_bf16 v[66:69], v[188:191], v[230:233], v[66:69]
	v_mfma_f32_16x16x32_bf16 v[82:85], v[180:183], v[230:233], v[82:85]
	v_mfma_f32_16x16x32_bf16 v[70:73], v[90:93], v[230:233], v[70:73]
	v_mfma_f32_16x16x32_bf16 v[86:89], v[74:77], v[230:233], v[86:89]
	s_setprio 0
	s_setprio 1
	v_mfma_f32_16x16x32_bf16 v[142:145], v[78:81], v[200:203], v[142:145]
	v_mfma_f32_16x16x32_bf16 v[134:137], v[94:97], v[200:203], v[134:137]
	v_mfma_f32_16x16x32_bf16 v[138:141], v[184:187], v[200:203], v[138:141]
	v_mfma_f32_16x16x32_bf16 v[130:133], v[192:195], v[200:203], v[130:133]
	v_mfma_f32_16x16x32_bf16 v[114:117], v[192:195], v[208:211], v[114:117]
	v_mfma_f32_16x16x32_bf16 v[122:125], v[184:187], v[208:211], v[122:125]
	v_mfma_f32_16x16x32_bf16 v[118:121], v[94:97], v[208:211], v[118:121]
	v_mfma_f32_16x16x32_bf16 v[126:129], v[78:81], v[208:211], v[126:129]
	v_mfma_f32_16x16x32_bf16 v[110:113], v[78:81], v[216:219], v[110:113]
	v_mfma_f32_16x16x32_bf16 v[102:105], v[94:97], v[216:219], v[102:105]
	v_mfma_f32_16x16x32_bf16 v[106:109], v[184:187], v[216:219], v[106:109]
	v_mfma_f32_16x16x32_bf16 v[98:101], v[192:195], v[216:219], v[98:101]
	v_mfma_f32_16x16x32_bf16 v[66:69], v[192:195], v[238:241], v[66:69]
	v_mfma_f32_16x16x32_bf16 v[82:85], v[184:187], v[238:241], v[82:85]
	v_mfma_f32_16x16x32_bf16 v[70:73], v[94:97], v[238:241], v[70:73]
	v_mfma_f32_16x16x32_bf16 v[86:89], v[78:81], v[238:241], v[86:89]
	s_setprio 0
	s_barrier
	s_add_i32 s83, s83, s37
	v_lshl_add_u64 v[168:169], s[56:57], 0, v[150:151]
	s_mov_b32 m0, s83
	ds_read_b128 v[196:199], v177 offset:16384
	ds_read_b128 v[200:203], v177 offset:17408
	ds_read_b128 v[204:207], v177 offset:18432
	ds_read_b128 v[208:211], v177 offset:19456
	ds_read_b128 v[212:215], v177 offset:20480
	ds_read_b128 v[216:219], v177 offset:21504
	ds_read_b128 v[230:233], v177 offset:22528
	ds_read_b128 v[238:241], v177 offset:23552
	global_load_lds_dwordx4 v[168:169], off
	s_add_i32 m0, s83, 0x2000
	s_add_u32 s84, s56, 0x40000
	v_lshl_add_u64 v[242:243], s[56:57], 0, v[146:147]
	s_addc_u32 s85, s57, 0
	s_add_i32 s0, s0, s37
	global_load_lds_dwordx4 v[242:243], off
	v_lshl_add_u64 v[244:245], s[84:85], 0, v[150:151]
	s_mov_b32 m0, s0
	v_lshl_add_u64 v[246:247], s[58:59], 0, v[148:149]
	global_load_lds_dwordx4 v[244:245], off
	v_lshl_add_u64 v[244:245], s[84:85], 0, v[146:147]
	s_add_i32 m0, s0, 0x2000
	s_nop 0
	global_load_lds_dwordx4 v[244:245], off
	v_lshl_add_u64 v[244:245], s[58:59], 0, v[152:153]
	s_mov_b32 m0, s61
	s_nop 0
	global_load_lds_dwordx4 v[244:245], off
	s_mov_b32 m0, s64
	s_nop 0
	global_load_lds_dwordx4 v[246:247], off
	s_waitcnt vmcnt(8)
	s_waitcnt lgkmcnt(0)
	s_barrier
	s_setprio 1
	s_waitcnt lgkmcnt(0)
	v_mfma_f32_16x16x32_bf16 v[62:65], v[74:77], v[196:199], v[62:65]
	v_mfma_f32_16x16x32_bf16 v[54:57], v[90:93], v[196:199], v[54:57]
	v_mfma_f32_16x16x32_bf16 v[58:61], v[180:183], v[196:199], v[58:61]
	v_mfma_f32_16x16x32_bf16 v[50:53], v[188:191], v[196:199], v[50:53]
	v_mfma_f32_16x16x32_bf16 v[34:37], v[188:191], v[204:207], v[34:37]
	v_mfma_f32_16x16x32_bf16 v[42:45], v[180:183], v[204:207], v[42:45]
	v_mfma_f32_16x16x32_bf16 v[38:41], v[90:93], v[204:207], v[38:41]
	v_mfma_f32_16x16x32_bf16 v[46:49], v[74:77], v[204:207], v[46:49]
	v_mfma_f32_16x16x32_bf16 v[30:33], v[74:77], v[212:215], v[30:33]
	v_mfma_f32_16x16x32_bf16 v[22:25], v[90:93], v[212:215], v[22:25]
	v_mfma_f32_16x16x32_bf16 v[26:29], v[180:183], v[212:215], v[26:29]
	v_mfma_f32_16x16x32_bf16 v[18:21], v[188:191], v[212:215], v[18:21]
	v_mfma_f32_16x16x32_bf16 v[2:5], v[188:191], v[230:233], v[2:5]
	v_mfma_f32_16x16x32_bf16 v[10:13], v[180:183], v[230:233], v[10:13]
	v_mfma_f32_16x16x32_bf16 v[6:9], v[90:93], v[230:233], v[6:9]
	v_mfma_f32_16x16x32_bf16 v[14:17], v[74:77], v[230:233], v[14:17]
	s_setprio 0
	s_setprio 1
	v_mfma_f32_16x16x32_bf16 v[62:65], v[78:81], v[200:203], v[62:65]
	v_mfma_f32_16x16x32_bf16 v[54:57], v[94:97], v[200:203], v[54:57]
	v_mfma_f32_16x16x32_bf16 v[58:61], v[184:187], v[200:203], v[58:61]
	v_mfma_f32_16x16x32_bf16 v[50:53], v[192:195], v[200:203], v[50:53]
	v_mfma_f32_16x16x32_bf16 v[34:37], v[192:195], v[208:211], v[34:37]
	v_mfma_f32_16x16x32_bf16 v[42:45], v[184:187], v[208:211], v[42:45]
	v_mfma_f32_16x16x32_bf16 v[38:41], v[94:97], v[208:211], v[38:41]
	v_mfma_f32_16x16x32_bf16 v[46:49], v[78:81], v[208:211], v[46:49]
	v_mfma_f32_16x16x32_bf16 v[30:33], v[78:81], v[216:219], v[30:33]
	v_mfma_f32_16x16x32_bf16 v[22:25], v[94:97], v[216:219], v[22:25]
	v_mfma_f32_16x16x32_bf16 v[26:29], v[184:187], v[216:219], v[26:29]
	v_mfma_f32_16x16x32_bf16 v[18:21], v[192:195], v[216:219], v[18:21]
	v_mfma_f32_16x16x32_bf16 v[2:5], v[192:195], v[238:241], v[2:5]
	v_mfma_f32_16x16x32_bf16 v[10:13], v[184:187], v[238:241], v[10:13]
	v_mfma_f32_16x16x32_bf16 v[6:9], v[94:97], v[238:241], v[6:9]
	v_mfma_f32_16x16x32_bf16 v[14:17], v[78:81], v[238:241], v[14:17]
	s_setprio 0
	s_barrier
	s_add_i32 s0, 0, 0x18000
	s_add_i32 s83, 0, 0x1c000
	v_add_u32_e32 v94, s0, v171
	v_add_u32_e32 v155, s83, v171
	ds_read_b128 v[74:77], v94
	ds_read_b128 v[78:81], v94 offset:1024
	ds_read_b128 v[90:93], v94 offset:2048
	ds_read_b128 v[94:97], v94 offset:3072
	ds_read_b128 v[180:183], v155
	ds_read_b128 v[184:187], v155 offset:1024
	ds_read_b128 v[188:191], v155 offset:2048
	ds_read_b128 v[192:195], v155 offset:3072
	s_add_u32 s58, s58, 0x40000
	s_addc_u32 s59, s59, 0
	s_mov_b32 m0, s65
	v_lshl_add_u64 v[248:249], s[58:59], 0, v[152:153]
	ds_read_b128 v[196:199], v177 offset:32768
	ds_read_b128 v[200:203], v177 offset:33792
	ds_read_b128 v[204:207], v177 offset:34816
	ds_read_b128 v[208:211], v177 offset:35840
	ds_read_b128 v[212:215], v177 offset:36864
	ds_read_b128 v[216:219], v177 offset:37888
	ds_read_b128 v[230:233], v177 offset:38912
	ds_read_b128 v[238:241], v177 offset:39936
	global_load_lds_dwordx4 v[248:249], off
	v_lshl_add_u64 v[248:249], s[58:59], 0, v[148:149]
	s_mov_b32 m0, s66
	s_nop 0
	global_load_lds_dwordx4 v[248:249], off
	s_waitcnt vmcnt(8)
	s_waitcnt lgkmcnt(0)
	s_barrier
	s_setprio 1
	s_waitcnt lgkmcnt(0)
	v_mfma_f32_16x16x32_bf16 v[142:145], v[74:77], v[196:199], v[142:145]
	v_mfma_f32_16x16x32_bf16 v[134:137], v[90:93], v[196:199], v[134:137]
	v_mfma_f32_16x16x32_bf16 v[138:141], v[180:183], v[196:199], v[138:141]
	v_mfma_f32_16x16x32_bf16 v[130:133], v[188:191], v[196:199], v[130:133]
	v_mfma_f32_16x16x32_bf16 v[114:117], v[188:191], v[204:207], v[114:117]
	v_mfma_f32_16x16x32_bf16 v[122:125], v[180:183], v[204:207], v[122:125]
	v_mfma_f32_16x16x32_bf16 v[118:121], v[90:93], v[204:207], v[118:121]
	v_mfma_f32_16x16x32_bf16 v[126:129], v[74:77], v[204:207], v[126:129]
	v_mfma_f32_16x16x32_bf16 v[110:113], v[74:77], v[212:215], v[110:113]
	v_mfma_f32_16x16x32_bf16 v[102:105], v[90:93], v[212:215], v[102:105]
	v_mfma_f32_16x16x32_bf16 v[106:109], v[180:183], v[212:215], v[106:109]
	v_mfma_f32_16x16x32_bf16 v[98:101], v[188:191], v[212:215], v[98:101]
	v_mfma_f32_16x16x32_bf16 v[66:69], v[188:191], v[230:233], v[66:69]
	v_mfma_f32_16x16x32_bf16 v[82:85], v[180:183], v[230:233], v[82:85]
	v_mfma_f32_16x16x32_bf16 v[70:73], v[90:93], v[230:233], v[70:73]
	v_mfma_f32_16x16x32_bf16 v[86:89], v[74:77], v[230:233], v[86:89]
	s_setprio 0
	s_setprio 1
	v_mfma_f32_16x16x32_bf16 v[142:145], v[78:81], v[200:203], v[142:145]
	v_mfma_f32_16x16x32_bf16 v[134:137], v[94:97], v[200:203], v[134:137]
	v_mfma_f32_16x16x32_bf16 v[138:141], v[184:187], v[200:203], v[138:141]
	v_mfma_f32_16x16x32_bf16 v[130:133], v[192:195], v[200:203], v[130:133]
	v_mfma_f32_16x16x32_bf16 v[114:117], v[192:195], v[208:211], v[114:117]
	v_mfma_f32_16x16x32_bf16 v[122:125], v[184:187], v[208:211], v[122:125]
	v_mfma_f32_16x16x32_bf16 v[118:121], v[94:97], v[208:211], v[118:121]
	v_mfma_f32_16x16x32_bf16 v[126:129], v[78:81], v[208:211], v[126:129]
	v_mfma_f32_16x16x32_bf16 v[110:113], v[78:81], v[216:219], v[110:113]
	v_mfma_f32_16x16x32_bf16 v[102:105], v[94:97], v[216:219], v[102:105]
	v_mfma_f32_16x16x32_bf16 v[106:109], v[184:187], v[216:219], v[106:109]
	v_mfma_f32_16x16x32_bf16 v[98:101], v[192:195], v[216:219], v[98:101]
	v_mfma_f32_16x16x32_bf16 v[66:69], v[192:195], v[238:241], v[66:69]
	v_mfma_f32_16x16x32_bf16 v[82:85], v[184:187], v[238:241], v[82:85]
	v_mfma_f32_16x16x32_bf16 v[70:73], v[94:97], v[238:241], v[70:73]
	v_mfma_f32_16x16x32_bf16 v[86:89], v[78:81], v[238:241], v[86:89]
	s_setprio 0
	s_barrier
	s_add_i32 s0, s0, s37
	v_lshl_add_u64 v[168:169], v[168:169], 0, s[76:77]
	s_mov_b32 m0, s0
	ds_read_b128 v[196:199], v177 offset:49152
	ds_read_b128 v[200:203], v177 offset:50176
	ds_read_b128 v[204:207], v177 offset:51200
	ds_read_b128 v[208:211], v177 offset:52224
	ds_read_b128 v[212:215], v177 offset:53248
	ds_read_b128 v[216:219], v177 offset:54272
	ds_read_b128 v[230:233], v177 offset:55296
	ds_read_b128 v[238:241], v177 offset:56320
	global_load_lds_dwordx4 v[168:169], off
	s_add_i32 m0, s0, 0x2000
	s_add_u32 s56, s56, 0x40080
	v_lshl_add_u64 v[168:169], v[242:243], 0, s[76:77]
	s_addc_u32 s57, s57, 0
	s_add_i32 s0, s83, s37
	global_load_lds_dwordx4 v[168:169], off
	v_lshl_add_u64 v[168:169], s[56:57], 0, v[150:151]
	s_mov_b32 m0, s0
	s_nop 0
	global_load_lds_dwordx4 v[168:169], off
	v_lshl_add_u64 v[168:169], s[56:57], 0, v[146:147]
	s_add_i32 m0, s0, 0x2000
	s_nop 0
	global_load_lds_dwordx4 v[168:169], off
	v_lshl_add_u64 v[168:169], v[244:245], 0, s[76:77]
	s_mov_b32 m0, s67
	s_nop 0
	global_load_lds_dwordx4 v[168:169], off
	v_lshl_add_u64 v[168:169], v[246:247], 0, s[76:77]
	s_mov_b32 m0, s68
	s_nop 0
	global_load_lds_dwordx4 v[168:169], off
	s_waitcnt vmcnt(8)
	s_waitcnt lgkmcnt(0)
	s_barrier
	s_setprio 1
	s_waitcnt lgkmcnt(0)
	v_mfma_f32_16x16x32_bf16 v[62:65], v[74:77], v[196:199], v[62:65]
	v_mfma_f32_16x16x32_bf16 v[54:57], v[90:93], v[196:199], v[54:57]
	v_mfma_f32_16x16x32_bf16 v[58:61], v[180:183], v[196:199], v[58:61]
	v_mfma_f32_16x16x32_bf16 v[50:53], v[188:191], v[196:199], v[50:53]
	v_mfma_f32_16x16x32_bf16 v[34:37], v[188:191], v[204:207], v[34:37]
	v_mfma_f32_16x16x32_bf16 v[42:45], v[180:183], v[204:207], v[42:45]
	v_mfma_f32_16x16x32_bf16 v[38:41], v[90:93], v[204:207], v[38:41]
	v_mfma_f32_16x16x32_bf16 v[46:49], v[74:77], v[204:207], v[46:49]
	v_mfma_f32_16x16x32_bf16 v[30:33], v[74:77], v[212:215], v[30:33]
	v_mfma_f32_16x16x32_bf16 v[22:25], v[90:93], v[212:215], v[22:25]
	v_mfma_f32_16x16x32_bf16 v[26:29], v[180:183], v[212:215], v[26:29]
	v_mfma_f32_16x16x32_bf16 v[18:21], v[188:191], v[212:215], v[18:21]
	v_mfma_f32_16x16x32_bf16 v[2:5], v[188:191], v[230:233], v[2:5]
	v_mfma_f32_16x16x32_bf16 v[10:13], v[180:183], v[230:233], v[10:13]
	v_mfma_f32_16x16x32_bf16 v[6:9], v[90:93], v[230:233], v[6:9]
	v_mfma_f32_16x16x32_bf16 v[14:17], v[74:77], v[230:233], v[14:17]
	s_setprio 0
	s_setprio 1
	v_mfma_f32_16x16x32_bf16 v[62:65], v[78:81], v[200:203], v[62:65]
	v_mfma_f32_16x16x32_bf16 v[54:57], v[94:97], v[200:203], v[54:57]
	v_mfma_f32_16x16x32_bf16 v[58:61], v[184:187], v[200:203], v[58:61]
	v_mfma_f32_16x16x32_bf16 v[50:53], v[192:195], v[200:203], v[50:53]
	v_mfma_f32_16x16x32_bf16 v[34:37], v[192:195], v[208:211], v[34:37]
	v_mfma_f32_16x16x32_bf16 v[42:45], v[184:187], v[208:211], v[42:45]
	v_mfma_f32_16x16x32_bf16 v[38:41], v[94:97], v[208:211], v[38:41]
	v_mfma_f32_16x16x32_bf16 v[46:49], v[78:81], v[208:211], v[46:49]
	v_mfma_f32_16x16x32_bf16 v[30:33], v[78:81], v[216:219], v[30:33]
	v_mfma_f32_16x16x32_bf16 v[22:25], v[94:97], v[216:219], v[22:25]
	v_mfma_f32_16x16x32_bf16 v[26:29], v[184:187], v[216:219], v[26:29]
	v_mfma_f32_16x16x32_bf16 v[18:21], v[192:195], v[216:219], v[18:21]
	v_mfma_f32_16x16x32_bf16 v[2:5], v[192:195], v[238:241], v[2:5]
	v_mfma_f32_16x16x32_bf16 v[10:13], v[184:187], v[238:241], v[10:13]
	v_mfma_f32_16x16x32_bf16 v[6:9], v[94:97], v[238:241], v[6:9]
	v_mfma_f32_16x16x32_bf16 v[14:17], v[78:81], v[238:241], v[14:17]
	s_setprio 0
	s_barrier
	s_add_i32 s82, s82, 2
	s_add_u32 s52, s52, 0x100
	s_addc_u32 s53, s53, 0
	s_add_u32 s73, s73, 0x100
	s_addc_u32 s75, s75, 0
	s_cmp_gt_u32 s82, 13
	s_cbranch_scc0 .LBB0_256
	s_and_b64 vcc, exec, s[10:11]
	s_cbranch_vccz .LBB0_259
	s_barrier

.LBB0_282:
	s_ashr_i32 s59, s58, 31
	s_lshl_b64 s[20:21], s[58:59], 19
	s_add_u32 s64, s26, s20
	s_addc_u32 s65, s27, s21
	s_and_b64 s[20:21], s[8:9], exec
	s_cselect_b32 s20, s65, s5
	s_cselect_b32 s21, s64, s4
	s_ashr_i32 s57, s56, 31
	s_lshl_b64 s[36:37], s[56:57], 19
	s_add_u32 s66, s35, s36
	s_addc_u32 s67, s40, s37
	s_and_b64 s[36:37], s[8:9], exec
	s_cselect_b32 s36, s67, s7
	s_cselect_b32 s37, s66, s6
	s_add_u32 s4, s4, 0x40080
	s_addc_u32 s5, s5, 0
	s_add_u32 s46, s6, 0x100
	s_addc_u32 s57, s7, 0
	s_mov_b32 s59, -2
	s_add_u32 s6, s4, 0xfffc0080
	s_addc_u32 s7, s5, -1
	s_add_i32 s82, 0, 0x10000
	s_cmp_eq_u32 s59, 12
	s_cselect_b32 s69, s20, s7
	s_cselect_b32 s68, s21, s6
	s_cselect_b32 s7, s36, s57
	s_cselect_b32 s6, s37, s46
	s_add_i32 s84, 0, 0x14000
	v_add_u32_e32 v142, s82, v202
	v_add_u32_e32 v158, s84, v202
	ds_read_b128 v[130:133], v142
	ds_read_b128 v[134:137], v142 offset:1024
	ds_read_b128 v[138:141], v142 offset:2048
	ds_read_b128 v[142:145], v142 offset:3072
	ds_read_b128 v[146:149], v158
	ds_read_b128 v[150:153], v158 offset:1024
	ds_read_b128 v[154:157], v158 offset:2048
	ds_read_b128 v[158:161], v158 offset:3072
	v_lshl_add_u64 v[218:219], s[4:5], 0, v[182:183]
	s_add_i32 m0, s87, 0xc000
	ds_read_b128 v[186:189], v204
	ds_read_b128 v[190:193], v204 offset:1024
	ds_read_b128 v[194:197], v204 offset:2048
	ds_read_b128 v[198:201], v204 offset:3072
	ds_read_b128 v[206:209], v204 offset:4096
	ds_read_b128 v[210:213], v204 offset:5120
	ds_read_b128 v[214:217], v204 offset:6144
	ds_read_b128 v[238:241], v204 offset:7168
	global_load_lds_dwordx4 v[218:219], off
	v_lshl_add_u64 v[218:219], s[4:5], 0, v[184:185]
	s_add_i32 m0, s87, 0xe000
	s_nop 0
	global_load_lds_dwordx4 v[218:219], off
	s_waitcnt vmcnt(8)
	s_waitcnt lgkmcnt(0)
	s_barrier
	s_setprio 1
	s_waitcnt lgkmcnt(0)
	v_mfma_f32_16x16x32_bf16 v[2:5], v[130:133], v[186:189], 0
	v_mfma_f32_16x16x32_bf16 v[6:9], v[138:141], v[186:189], 0
	v_mfma_f32_16x16x32_bf16 v[14:17], v[146:149], v[186:189], 0
	v_mfma_f32_16x16x32_bf16 v[10:13], v[154:157], v[186:189], 0
	v_mfma_f32_16x16x32_bf16 v[18:21], v[154:157], v[194:197], 0
	v_mfma_f32_16x16x32_bf16 v[22:25], v[146:149], v[194:197], 0
	v_mfma_f32_16x16x32_bf16 v[26:29], v[138:141], v[194:197], 0
	v_mfma_f32_16x16x32_bf16 v[30:33], v[130:133], v[194:197], 0
	v_mfma_f32_16x16x32_bf16 v[34:37], v[130:133], v[206:209], 0
	v_mfma_f32_16x16x32_bf16 v[42:45], v[138:141], v[206:209], 0
	v_mfma_f32_16x16x32_bf16 v[46:49], v[146:149], v[206:209], 0
	v_mfma_f32_16x16x32_bf16 v[38:41], v[154:157], v[206:209], 0
	v_mfma_f32_16x16x32_bf16 v[50:53], v[154:157], v[214:217], 0
	v_mfma_f32_16x16x32_bf16 v[54:57], v[146:149], v[214:217], 0
	v_mfma_f32_16x16x32_bf16 v[58:61], v[138:141], v[214:217], 0
	v_mfma_f32_16x16x32_bf16 v[62:65], v[130:133], v[214:217], 0
	s_setprio 0
	s_setprio 1
	v_mfma_f32_16x16x32_bf16 v[2:5], v[134:137], v[190:193], v[2:5]
	v_mfma_f32_16x16x32_bf16 v[6:9], v[142:145], v[190:193], v[6:9]
	v_mfma_f32_16x16x32_bf16 v[14:17], v[150:153], v[190:193], v[14:17]
	v_mfma_f32_16x16x32_bf16 v[10:13], v[158:161], v[190:193], v[10:13]
	v_mfma_f32_16x16x32_bf16 v[18:21], v[158:161], v[198:201], v[18:21]
	v_mfma_f32_16x16x32_bf16 v[22:25], v[150:153], v[198:201], v[22:25]
	v_mfma_f32_16x16x32_bf16 v[26:29], v[142:145], v[198:201], v[26:29]
	v_mfma_f32_16x16x32_bf16 v[30:33], v[134:137], v[198:201], v[30:33]
	v_mfma_f32_16x16x32_bf16 v[34:37], v[134:137], v[210:213], v[34:37]
	v_mfma_f32_16x16x32_bf16 v[42:45], v[142:145], v[210:213], v[42:45]
	v_mfma_f32_16x16x32_bf16 v[46:49], v[150:153], v[210:213], v[46:49]
	v_mfma_f32_16x16x32_bf16 v[38:41], v[158:161], v[210:213], v[38:41]
	v_mfma_f32_16x16x32_bf16 v[50:53], v[158:161], v[238:241], v[50:53]
	v_mfma_f32_16x16x32_bf16 v[54:57], v[150:153], v[238:241], v[54:57]
	v_mfma_f32_16x16x32_bf16 v[58:61], v[142:145], v[238:241], v[58:61]
	v_mfma_f32_16x16x32_bf16 v[62:65], v[134:137], v[238:241], v[62:65]
	s_setprio 0
	s_barrier
	s_add_i32 s82, s82, s41
	v_lshl_add_u64 v[218:219], s[6:7], 0, v[164:165]
	s_mov_b32 m0, s82
	ds_read_b128 v[186:189], v204 offset:16384
	ds_read_b128 v[190:193], v204 offset:17408
	ds_read_b128 v[194:197], v204 offset:18432
	ds_read_b128 v[198:201], v204 offset:19456
	ds_read_b128 v[206:209], v204 offset:20480
	ds_read_b128 v[210:213], v204 offset:21504
	ds_read_b128 v[214:217], v204 offset:22528
	ds_read_b128 v[238:241], v204 offset:23552
	global_load_lds_dwordx4 v[218:219], off
	s_add_i32 m0, s82, 0x2000
	s_add_u32 s82, s6, 0x40000
	v_lshl_add_u64 v[230:231], s[6:7], 0, v[162:163]
	s_addc_u32 s83, s7, 0
	s_add_i32 s84, s84, s41
	global_load_lds_dwordx4 v[230:231], off
	v_lshl_add_u64 v[232:233], s[82:83], 0, v[164:165]
	s_mov_b32 m0, s84
	v_lshl_add_u64 v[242:243], s[68:69], 0, v[162:163]
	global_load_lds_dwordx4 v[232:233], off
	v_lshl_add_u64 v[232:233], s[82:83], 0, v[162:163]
	s_add_i32 m0, s84, 0x2000
	s_nop 0
	global_load_lds_dwordx4 v[232:233], off
	v_lshl_add_u64 v[232:233], s[68:69], 0, v[164:165]
	s_mov_b32 m0, s87
	s_nop 0
	global_load_lds_dwordx4 v[232:233], off
	s_mov_b32 m0, s75
	s_nop 0
	global_load_lds_dwordx4 v[242:243], off
	s_waitcnt vmcnt(8)
	s_waitcnt lgkmcnt(0)
	s_barrier
	s_setprio 1
	s_waitcnt lgkmcnt(0)
	v_mfma_f32_16x16x32_bf16 v[74:77], v[130:133], v[186:189], 0
	v_mfma_f32_16x16x32_bf16 v[70:73], v[138:141], v[186:189], 0
	v_mfma_f32_16x16x32_bf16 v[78:81], v[146:149], v[186:189], 0
	v_mfma_f32_16x16x32_bf16 v[66:69], v[154:157], v[186:189], 0
	v_mfma_f32_16x16x32_bf16 v[82:85], v[154:157], v[194:197], 0
	v_mfma_f32_16x16x32_bf16 v[86:89], v[146:149], v[194:197], 0
	v_mfma_f32_16x16x32_bf16 v[90:93], v[138:141], v[194:197], 0
	v_mfma_f32_16x16x32_bf16 v[94:97], v[130:133], v[194:197], 0
	v_mfma_f32_16x16x32_bf16 v[106:109], v[130:133], v[206:209], 0
	v_mfma_f32_16x16x32_bf16 v[102:105], v[138:141], v[206:209], 0
	v_mfma_f32_16x16x32_bf16 v[110:113], v[146:149], v[206:209], 0
	v_mfma_f32_16x16x32_bf16 v[98:101], v[154:157], v[206:209], 0
	v_mfma_f32_16x16x32_bf16 v[126:129], v[154:157], v[214:217], 0
	v_mfma_f32_16x16x32_bf16 v[122:125], v[146:149], v[214:217], 0
	v_mfma_f32_16x16x32_bf16 v[114:117], v[138:141], v[214:217], 0
	v_mfma_f32_16x16x32_bf16 v[118:121], v[130:133], v[214:217], 0
	s_setprio 0
	s_setprio 1
	v_mfma_f32_16x16x32_bf16 v[74:77], v[134:137], v[190:193], v[74:77]
	v_mfma_f32_16x16x32_bf16 v[70:73], v[142:145], v[190:193], v[70:73]
	v_mfma_f32_16x16x32_bf16 v[78:81], v[150:153], v[190:193], v[78:81]
	v_mfma_f32_16x16x32_bf16 v[66:69], v[158:161], v[190:193], v[66:69]
	v_mfma_f32_16x16x32_bf16 v[82:85], v[158:161], v[198:201], v[82:85]
	v_mfma_f32_16x16x32_bf16 v[86:89], v[150:153], v[198:201], v[86:89]
	v_mfma_f32_16x16x32_bf16 v[90:93], v[142:145], v[198:201], v[90:93]
	v_mfma_f32_16x16x32_bf16 v[94:97], v[134:137], v[198:201], v[94:97]
	v_mfma_f32_16x16x32_bf16 v[106:109], v[134:137], v[210:213], v[106:109]
	v_mfma_f32_16x16x32_bf16 v[102:105], v[142:145], v[210:213], v[102:105]
	v_mfma_f32_16x16x32_bf16 v[110:113], v[150:153], v[210:213], v[110:113]
	v_mfma_f32_16x16x32_bf16 v[98:101], v[158:161], v[210:213], v[98:101]
	v_mfma_f32_16x16x32_bf16 v[126:129], v[158:161], v[238:241], v[126:129]
	v_mfma_f32_16x16x32_bf16 v[122:125], v[150:153], v[238:241], v[122:125]
	v_mfma_f32_16x16x32_bf16 v[114:117], v[142:145], v[238:241], v[114:117]
	v_mfma_f32_16x16x32_bf16 v[118:121], v[134:137], v[238:241], v[118:121]
	s_setprio 0
	s_barrier
	s_add_i32 s82, 0, 0x18000
	s_add_i32 s83, 0, 0x1c000
	v_add_u32_e32 v142, s82, v202
	v_add_u32_e32 v158, s83, v202
	ds_read_b128 v[130:133], v142
	ds_read_b128 v[134:137], v142 offset:1024
	ds_read_b128 v[138:141], v142 offset:2048
	ds_read_b128 v[142:145], v142 offset:3072
	ds_read_b128 v[146:149], v158
	ds_read_b128 v[150:153], v158 offset:1024
	ds_read_b128 v[154:157], v158 offset:2048
	ds_read_b128 v[158:161], v158 offset:3072
	s_add_u32 s68, s68, 0x40000
	s_addc_u32 s69, s69, 0
	s_mov_b32 m0, s72
	v_lshl_add_u64 v[244:245], s[68:69], 0, v[164:165]
	ds_read_b128 v[186:189], v204 offset:32768
	ds_read_b128 v[190:193], v204 offset:33792
	ds_read_b128 v[194:197], v204 offset:34816
	ds_read_b128 v[198:201], v204 offset:35840
	ds_read_b128 v[206:209], v204 offset:36864
	ds_read_b128 v[210:213], v204 offset:37888
	ds_read_b128 v[214:217], v204 offset:38912
	ds_read_b128 v[238:241], v204 offset:39936
	global_load_lds_dwordx4 v[244:245], off
	v_lshl_add_u64 v[244:245], s[68:69], 0, v[162:163]
	s_mov_b32 m0, s73
	s_nop 0
	global_load_lds_dwordx4 v[244:245], off
	s_waitcnt vmcnt(8)
	s_waitcnt lgkmcnt(0)
	s_barrier
	s_setprio 1
	s_waitcnt lgkmcnt(0)
	v_mfma_f32_16x16x32_bf16 v[2:5], v[130:133], v[186:189], v[2:5]
	v_mfma_f32_16x16x32_bf16 v[6:9], v[138:141], v[186:189], v[6:9]
	v_mfma_f32_16x16x32_bf16 v[14:17], v[146:149], v[186:189], v[14:17]
	v_mfma_f32_16x16x32_bf16 v[10:13], v[154:157], v[186:189], v[10:13]
	v_mfma_f32_16x16x32_bf16 v[18:21], v[154:157], v[194:197], v[18:21]
	v_mfma_f32_16x16x32_bf16 v[22:25], v[146:149], v[194:197], v[22:25]
	v_mfma_f32_16x16x32_bf16 v[26:29], v[138:141], v[194:197], v[26:29]
	v_mfma_f32_16x16x32_bf16 v[30:33], v[130:133], v[194:197], v[30:33]
	v_mfma_f32_16x16x32_bf16 v[34:37], v[130:133], v[206:209], v[34:37]
	v_mfma_f32_16x16x32_bf16 v[42:45], v[138:141], v[206:209], v[42:45]
	v_mfma_f32_16x16x32_bf16 v[46:49], v[146:149], v[206:209], v[46:49]
	v_mfma_f32_16x16x32_bf16 v[38:41], v[154:157], v[206:209], v[38:41]
	v_mfma_f32_16x16x32_bf16 v[50:53], v[154:157], v[214:217], v[50:53]
	v_mfma_f32_16x16x32_bf16 v[54:57], v[146:149], v[214:217], v[54:57]
	v_mfma_f32_16x16x32_bf16 v[58:61], v[138:141], v[214:217], v[58:61]
	v_mfma_f32_16x16x32_bf16 v[62:65], v[130:133], v[214:217], v[62:65]
	s_setprio 0
	s_setprio 1
	v_mfma_f32_16x16x32_bf16 v[2:5], v[134:137], v[190:193], v[2:5]
	v_mfma_f32_16x16x32_bf16 v[6:9], v[142:145], v[190:193], v[6:9]
	v_mfma_f32_16x16x32_bf16 v[14:17], v[150:153], v[190:193], v[14:17]
	v_mfma_f32_16x16x32_bf16 v[10:13], v[158:161], v[190:193], v[10:13]
	v_mfma_f32_16x16x32_bf16 v[18:21], v[158:161], v[198:201], v[18:21]
	v_mfma_f32_16x16x32_bf16 v[22:25], v[150:153], v[198:201], v[22:25]
	v_mfma_f32_16x16x32_bf16 v[26:29], v[142:145], v[198:201], v[26:29]
	v_mfma_f32_16x16x32_bf16 v[30:33], v[134:137], v[198:201], v[30:33]
	v_mfma_f32_16x16x32_bf16 v[34:37], v[134:137], v[210:213], v[34:37]
	v_mfma_f32_16x16x32_bf16 v[42:45], v[142:145], v[210:213], v[42:45]
	v_mfma_f32_16x16x32_bf16 v[46:49], v[150:153], v[210:213], v[46:49]
	v_mfma_f32_16x16x32_bf16 v[38:41], v[158:161], v[210:213], v[38:41]
	v_mfma_f32_16x16x32_bf16 v[50:53], v[158:161], v[238:241], v[50:53]
	v_mfma_f32_16x16x32_bf16 v[54:57], v[150:153], v[238:241], v[54:57]
	v_mfma_f32_16x16x32_bf16 v[58:61], v[142:145], v[238:241], v[58:61]
	v_mfma_f32_16x16x32_bf16 v[62:65], v[134:137], v[238:241], v[62:65]
	s_setprio 0
	s_barrier
	s_add_i32 s68, s82, s41
	v_lshl_add_u64 v[218:219], v[218:219], 0, s[76:77]
	s_mov_b32 m0, s68
	ds_read_b128 v[186:189], v204 offset:49152
	ds_read_b128 v[190:193], v204 offset:50176
	ds_read_b128 v[194:197], v204 offset:51200
	ds_read_b128 v[198:201], v204 offset:52224
	ds_read_b128 v[206:209], v204 offset:53248
	ds_read_b128 v[210:213], v204 offset:54272
	ds_read_b128 v[214:217], v204 offset:55296
	ds_read_b128 v[238:241], v204 offset:56320
	global_load_lds_dwordx4 v[218:219], off
	s_add_i32 m0, s68, 0x2000
	s_add_u32 s6, s6, 0x40080
	v_lshl_add_u64 v[218:219], v[230:231], 0, s[76:77]
	s_addc_u32 s7, s7, 0
	s_add_i32 s68, s83, s41
	global_load_lds_dwordx4 v[218:219], off
	v_lshl_add_u64 v[218:219], s[6:7], 0, v[164:165]
	s_mov_b32 m0, s68
	s_nop 0
	global_load_lds_dwordx4 v[218:219], off
	v_lshl_add_u64 v[218:219], s[6:7], 0, v[162:163]
	s_add_i32 m0, s68, 0x2000
	s_nop 0
	global_load_lds_dwordx4 v[218:219], off
	v_lshl_add_u64 v[218:219], v[232:233], 0, s[76:77]
	s_mov_b32 m0, s34
	s_nop 0
	global_load_lds_dwordx4 v[218:219], off
	v_lshl_add_u64 v[218:219], v[242:243], 0, s[76:77]
	s_mov_b32 m0, s30
	s_nop 0
	global_load_lds_dwordx4 v[218:219], off
	s_waitcnt vmcnt(8)
	s_waitcnt lgkmcnt(0)
	s_barrier
	s_setprio 1
	s_waitcnt lgkmcnt(0)
	v_mfma_f32_16x16x32_bf16 v[74:77], v[130:133], v[186:189], v[74:77]
	v_mfma_f32_16x16x32_bf16 v[70:73], v[138:141], v[186:189], v[70:73]
	v_mfma_f32_16x16x32_bf16 v[78:81], v[146:149], v[186:189], v[78:81]
	v_mfma_f32_16x16x32_bf16 v[66:69], v[154:157], v[186:189], v[66:69]
	v_mfma_f32_16x16x32_bf16 v[82:85], v[154:157], v[194:197], v[82:85]
	v_mfma_f32_16x16x32_bf16 v[86:89], v[146:149], v[194:197], v[86:89]
	v_mfma_f32_16x16x32_bf16 v[90:93], v[138:141], v[194:197], v[90:93]
	v_mfma_f32_16x16x32_bf16 v[94:97], v[130:133], v[194:197], v[94:97]
	v_mfma_f32_16x16x32_bf16 v[106:109], v[130:133], v[206:209], v[106:109]
	v_mfma_f32_16x16x32_bf16 v[102:105], v[138:141], v[206:209], v[102:105]
	v_mfma_f32_16x16x32_bf16 v[110:113], v[146:149], v[206:209], v[110:113]
	v_mfma_f32_16x16x32_bf16 v[98:101], v[154:157], v[206:209], v[98:101]
	v_mfma_f32_16x16x32_bf16 v[126:129], v[154:157], v[214:217], v[126:129]
	v_mfma_f32_16x16x32_bf16 v[122:125], v[146:149], v[214:217], v[122:125]
	v_mfma_f32_16x16x32_bf16 v[114:117], v[138:141], v[214:217], v[114:117]
	v_mfma_f32_16x16x32_bf16 v[118:121], v[130:133], v[214:217], v[118:121]
	s_setprio 0
	s_setprio 1
	v_mfma_f32_16x16x32_bf16 v[74:77], v[134:137], v[190:193], v[74:77]
	v_mfma_f32_16x16x32_bf16 v[70:73], v[142:145], v[190:193], v[70:73]
	v_mfma_f32_16x16x32_bf16 v[78:81], v[150:153], v[190:193], v[78:81]
	v_mfma_f32_16x16x32_bf16 v[66:69], v[158:161], v[190:193], v[66:69]
	v_mfma_f32_16x16x32_bf16 v[82:85], v[158:161], v[198:201], v[82:85]
	v_mfma_f32_16x16x32_bf16 v[86:89], v[150:153], v[198:201], v[86:89]
	v_mfma_f32_16x16x32_bf16 v[90:93], v[142:145], v[198:201], v[90:93]
	v_mfma_f32_16x16x32_bf16 v[94:97], v[134:137], v[198:201], v[94:97]
	v_mfma_f32_16x16x32_bf16 v[106:109], v[134:137], v[210:213], v[106:109]
	v_mfma_f32_16x16x32_bf16 v[102:105], v[142:145], v[210:213], v[102:105]
	v_mfma_f32_16x16x32_bf16 v[110:113], v[150:153], v[210:213], v[110:113]
	v_mfma_f32_16x16x32_bf16 v[98:101], v[158:161], v[210:213], v[98:101]
	v_mfma_f32_16x16x32_bf16 v[126:129], v[158:161], v[238:241], v[126:129]
	v_mfma_f32_16x16x32_bf16 v[122:125], v[150:153], v[238:241], v[122:125]
	v_mfma_f32_16x16x32_bf16 v[114:117], v[142:145], v[238:241], v[114:117]
	v_mfma_f32_16x16x32_bf16 v[118:121], v[134:137], v[238:241], v[118:121]
	s_setprio 0
	s_barrier
	s_add_i32 s59, s59, 2
	s_add_u32 s4, s4, 0x100
	s_addc_u32 s5, s5, 0
	s_add_u32 s46, s46, 0x100
	s_addc_u32 s57, s57, 0
.LBB0_283:
	s_add_u32 s6, s4, 0xfffc0080
	s_addc_u32 s7, s5, -1
	s_add_i32 s82, 0, 0x10000
	s_cmp_eq_u32 s59, 12
	s_cselect_b32 s69, s20, s7
	s_cselect_b32 s68, s21, s6
	s_cselect_b32 s7, s36, s57
	s_cselect_b32 s6, s37, s46
	s_add_i32 s84, 0, 0x14000
	v_add_u32_e32 v142, s82, v202
	v_add_u32_e32 v158, s84, v202
	ds_read_b128 v[130:133], v142
	ds_read_b128 v[134:137], v142 offset:1024
	ds_read_b128 v[138:141], v142 offset:2048
	ds_read_b128 v[142:145], v142 offset:3072
	ds_read_b128 v[146:149], v158
	ds_read_b128 v[150:153], v158 offset:1024
	ds_read_b128 v[154:157], v158 offset:2048
	ds_read_b128 v[158:161], v158 offset:3072
	v_lshl_add_u64 v[218:219], s[4:5], 0, v[182:183]
	s_add_i32 m0, s87, 0xc000
	ds_read_b128 v[186:189], v204
	ds_read_b128 v[190:193], v204 offset:1024
	ds_read_b128 v[194:197], v204 offset:2048
	ds_read_b128 v[198:201], v204 offset:3072
	ds_read_b128 v[206:209], v204 offset:4096
	ds_read_b128 v[210:213], v204 offset:5120
	ds_read_b128 v[214:217], v204 offset:6144
	ds_read_b128 v[238:241], v204 offset:7168
	global_load_lds_dwordx4 v[218:219], off
	v_lshl_add_u64 v[218:219], s[4:5], 0, v[184:185]
	s_add_i32 m0, s87, 0xe000
	s_nop 0
	global_load_lds_dwordx4 v[218:219], off
	s_waitcnt vmcnt(8)
	s_waitcnt lgkmcnt(0)
	s_barrier
	s_setprio 1
	s_waitcnt lgkmcnt(0)
	v_mfma_f32_16x16x32_bf16 v[2:5], v[130:133], v[186:189], v[2:5]
	v_mfma_f32_16x16x32_bf16 v[6:9], v[138:141], v[186:189], v[6:9]
	v_mfma_f32_16x16x32_bf16 v[14:17], v[146:149], v[186:189], v[14:17]
	v_mfma_f32_16x16x32_bf16 v[10:13], v[154:157], v[186:189], v[10:13]
	v_mfma_f32_16x16x32_bf16 v[18:21], v[154:157], v[194:197], v[18:21]
	v_mfma_f32_16x16x32_bf16 v[22:25], v[146:149], v[194:197], v[22:25]
	v_mfma_f32_16x16x32_bf16 v[26:29], v[138:141], v[194:197], v[26:29]
	v_mfma_f32_16x16x32_bf16 v[30:33], v[130:133], v[194:197], v[30:33]
	v_mfma_f32_16x16x32_bf16 v[34:37], v[130:133], v[206:209], v[34:37]
	v_mfma_f32_16x16x32_bf16 v[42:45], v[138:141], v[206:209], v[42:45]
	v_mfma_f32_16x16x32_bf16 v[46:49], v[146:149], v[206:209], v[46:49]
	v_mfma_f32_16x16x32_bf16 v[38:41], v[154:157], v[206:209], v[38:41]
	v_mfma_f32_16x16x32_bf16 v[50:53], v[154:157], v[214:217], v[50:53]
	v_mfma_f32_16x16x32_bf16 v[54:57], v[146:149], v[214:217], v[54:57]
	v_mfma_f32_16x16x32_bf16 v[58:61], v[138:141], v[214:217], v[58:61]
	v_mfma_f32_16x16x32_bf16 v[62:65], v[130:133], v[214:217], v[62:65]
	s_setprio 0
	s_setprio 1
	v_mfma_f32_16x16x32_bf16 v[2:5], v[134:137], v[190:193], v[2:5]
	v_mfma_f32_16x16x32_bf16 v[6:9], v[142:145], v[190:193], v[6:9]
	v_mfma_f32_16x16x32_bf16 v[14:17], v[150:153], v[190:193], v[14:17]
	v_mfma_f32_16x16x32_bf16 v[10:13], v[158:161], v[190:193], v[10:13]
	v_mfma_f32_16x16x32_bf16 v[18:21], v[158:161], v[198:201], v[18:21]
	v_mfma_f32_16x16x32_bf16 v[22:25], v[150:153], v[198:201], v[22:25]
	v_mfma_f32_16x16x32_bf16 v[26:29], v[142:145], v[198:201], v[26:29]
	v_mfma_f32_16x16x32_bf16 v[30:33], v[134:137], v[198:201], v[30:33]
	v_mfma_f32_16x16x32_bf16 v[34:37], v[134:137], v[210:213], v[34:37]
	v_mfma_f32_16x16x32_bf16 v[42:45], v[142:145], v[210:213], v[42:45]
	v_mfma_f32_16x16x32_bf16 v[46:49], v[150:153], v[210:213], v[46:49]
	v_mfma_f32_16x16x32_bf16 v[38:41], v[158:161], v[210:213], v[38:41]
	v_mfma_f32_16x16x32_bf16 v[50:53], v[158:161], v[238:241], v[50:53]
	v_mfma_f32_16x16x32_bf16 v[54:57], v[150:153], v[238:241], v[54:57]
	v_mfma_f32_16x16x32_bf16 v[58:61], v[142:145], v[238:241], v[58:61]
	v_mfma_f32_16x16x32_bf16 v[62:65], v[134:137], v[238:241], v[62:65]
	s_setprio 0
	s_barrier
	s_add_i32 s82, s82, s41
	v_lshl_add_u64 v[218:219], s[6:7], 0, v[164:165]
	s_mov_b32 m0, s82
	ds_read_b128 v[186:189], v204 offset:16384
	ds_read_b128 v[190:193], v204 offset:17408
	ds_read_b128 v[194:197], v204 offset:18432
	ds_read_b128 v[198:201], v204 offset:19456
	ds_read_b128 v[206:209], v204 offset:20480
	ds_read_b128 v[210:213], v204 offset:21504
	ds_read_b128 v[214:217], v204 offset:22528
	ds_read_b128 v[238:241], v204 offset:23552
	global_load_lds_dwordx4 v[218:219], off
	s_add_i32 m0, s82, 0x2000
	s_add_u32 s82, s6, 0x40000
	v_lshl_add_u64 v[230:231], s[6:7], 0, v[162:163]
	s_addc_u32 s83, s7, 0
	s_add_i32 s84, s84, s41
	global_load_lds_dwordx4 v[230:231], off
	v_lshl_add_u64 v[232:233], s[82:83], 0, v[164:165]
	s_mov_b32 m0, s84
	v_lshl_add_u64 v[242:243], s[68:69], 0, v[162:163]
	global_load_lds_dwordx4 v[232:233], off
	v_lshl_add_u64 v[232:233], s[82:83], 0, v[162:163]
	s_add_i32 m0, s84, 0x2000
	s_nop 0
	global_load_lds_dwordx4 v[232:233], off
	v_lshl_add_u64 v[232:233], s[68:69], 0, v[164:165]
	s_mov_b32 m0, s87
	s_nop 0
	global_load_lds_dwordx4 v[232:233], off
	s_mov_b32 m0, s75
	s_nop 0
	global_load_lds_dwordx4 v[242:243], off
	s_waitcnt vmcnt(8)
	s_waitcnt lgkmcnt(0)
	s_barrier
	s_setprio 1
	s_waitcnt lgkmcnt(0)
	v_mfma_f32_16x16x32_bf16 v[74:77], v[130:133], v[186:189], v[74:77]
	v_mfma_f32_16x16x32_bf16 v[70:73], v[138:141], v[186:189], v[70:73]
	v_mfma_f32_16x16x32_bf16 v[78:81], v[146:149], v[186:189], v[78:81]
	v_mfma_f32_16x16x32_bf16 v[66:69], v[154:157], v[186:189], v[66:69]
	v_mfma_f32_16x16x32_bf16 v[82:85], v[154:157], v[194:197], v[82:85]
	v_mfma_f32_16x16x32_bf16 v[86:89], v[146:149], v[194:197], v[86:89]
	v_mfma_f32_16x16x32_bf16 v[90:93], v[138:141], v[194:197], v[90:93]
	v_mfma_f32_16x16x32_bf16 v[94:97], v[130:133], v[194:197], v[94:97]
	v_mfma_f32_16x16x32_bf16 v[106:109], v[130:133], v[206:209], v[106:109]
	v_mfma_f32_16x16x32_bf16 v[102:105], v[138:141], v[206:209], v[102:105]
	v_mfma_f32_16x16x32_bf16 v[110:113], v[146:149], v[206:209], v[110:113]
	v_mfma_f32_16x16x32_bf16 v[98:101], v[154:157], v[206:209], v[98:101]
	v_mfma_f32_16x16x32_bf16 v[126:129], v[154:157], v[214:217], v[126:129]
	v_mfma_f32_16x16x32_bf16 v[122:125], v[146:149], v[214:217], v[122:125]
	v_mfma_f32_16x16x32_bf16 v[114:117], v[138:141], v[214:217], v[114:117]
	v_mfma_f32_16x16x32_bf16 v[118:121], v[130:133], v[214:217], v[118:121]
	s_setprio 0
	s_setprio 1
	v_mfma_f32_16x16x32_bf16 v[74:77], v[134:137], v[190:193], v[74:77]
	v_mfma_f32_16x16x32_bf16 v[70:73], v[142:145], v[190:193], v[70:73]
	v_mfma_f32_16x16x32_bf16 v[78:81], v[150:153], v[190:193], v[78:81]
	v_mfma_f32_16x16x32_bf16 v[66:69], v[158:161], v[190:193], v[66:69]
	v_mfma_f32_16x16x32_bf16 v[82:85], v[158:161], v[198:201], v[82:85]
	v_mfma_f32_16x16x32_bf16 v[86:89], v[150:153], v[198:201], v[86:89]
	v_mfma_f32_16x16x32_bf16 v[90:93], v[142:145], v[198:201], v[90:93]
	v_mfma_f32_16x16x32_bf16 v[94:97], v[134:137], v[198:201], v[94:97]
	v_mfma_f32_16x16x32_bf16 v[106:109], v[134:137], v[210:213], v[106:109]
	v_mfma_f32_16x16x32_bf16 v[102:105], v[142:145], v[210:213], v[102:105]
	v_mfma_f32_16x16x32_bf16 v[110:113], v[150:153], v[210:213], v[110:113]
	v_mfma_f32_16x16x32_bf16 v[98:101], v[158:161], v[210:213], v[98:101]
	v_mfma_f32_16x16x32_bf16 v[126:129], v[158:161], v[238:241], v[126:129]
	v_mfma_f32_16x16x32_bf16 v[122:125], v[150:153], v[238:241], v[122:125]
	v_mfma_f32_16x16x32_bf16 v[114:117], v[142:145], v[238:241], v[114:117]
	v_mfma_f32_16x16x32_bf16 v[118:121], v[134:137], v[238:241], v[118:121]
	s_setprio 0
	s_barrier
	s_add_i32 s82, 0, 0x18000
	s_add_i32 s83, 0, 0x1c000
	v_add_u32_e32 v142, s82, v202
	v_add_u32_e32 v158, s83, v202
	ds_read_b128 v[130:133], v142
	ds_read_b128 v[134:137], v142 offset:1024
	ds_read_b128 v[138:141], v142 offset:2048
	ds_read_b128 v[142:145], v142 offset:3072
	ds_read_b128 v[146:149], v158
	ds_read_b128 v[150:153], v158 offset:1024
	ds_read_b128 v[154:157], v158 offset:2048
	ds_read_b128 v[158:161], v158 offset:3072
	s_add_u32 s68, s68, 0x40000
	s_addc_u32 s69, s69, 0
	s_mov_b32 m0, s72
	v_lshl_add_u64 v[244:245], s[68:69], 0, v[164:165]
	ds_read_b128 v[186:189], v204 offset:32768
	ds_read_b128 v[190:193], v204 offset:33792
	ds_read_b128 v[194:197], v204 offset:34816
	ds_read_b128 v[198:201], v204 offset:35840
	ds_read_b128 v[206:209], v204 offset:36864
	ds_read_b128 v[210:213], v204 offset:37888
	ds_read_b128 v[214:217], v204 offset:38912
	ds_read_b128 v[238:241], v204 offset:39936
	global_load_lds_dwordx4 v[244:245], off
	v_lshl_add_u64 v[244:245], s[68:69], 0, v[162:163]
	s_mov_b32 m0, s73
	s_nop 0
	global_load_lds_dwordx4 v[244:245], off
	s_waitcnt vmcnt(8)
	s_waitcnt lgkmcnt(0)
	s_barrier
	s_setprio 1
	s_waitcnt lgkmcnt(0)
	v_mfma_f32_16x16x32_bf16 v[2:5], v[130:133], v[186:189], v[2:5]
	v_mfma_f32_16x16x32_bf16 v[6:9], v[138:141], v[186:189], v[6:9]
	v_mfma_f32_16x16x32_bf16 v[14:17], v[146:149], v[186:189], v[14:17]
	v_mfma_f32_16x16x32_bf16 v[10:13], v[154:157], v[186:189], v[10:13]
	v_mfma_f32_16x16x32_bf16 v[18:21], v[154:157], v[194:197], v[18:21]
	v_mfma_f32_16x16x32_bf16 v[22:25], v[146:149], v[194:197], v[22:25]
	v_mfma_f32_16x16x32_bf16 v[26:29], v[138:141], v[194:197], v[26:29]
	v_mfma_f32_16x16x32_bf16 v[30:33], v[130:133], v[194:197], v[30:33]
	v_mfma_f32_16x16x32_bf16 v[34:37], v[130:133], v[206:209], v[34:37]
	v_mfma_f32_16x16x32_bf16 v[42:45], v[138:141], v[206:209], v[42:45]
	v_mfma_f32_16x16x32_bf16 v[46:49], v[146:149], v[206:209], v[46:49]
	v_mfma_f32_16x16x32_bf16 v[38:41], v[154:157], v[206:209], v[38:41]
	v_mfma_f32_16x16x32_bf16 v[50:53], v[154:157], v[214:217], v[50:53]
	v_mfma_f32_16x16x32_bf16 v[54:57], v[146:149], v[214:217], v[54:57]
	v_mfma_f32_16x16x32_bf16 v[58:61], v[138:141], v[214:217], v[58:61]
	v_mfma_f32_16x16x32_bf16 v[62:65], v[130:133], v[214:217], v[62:65]
	s_setprio 0
	s_setprio 1
	v_mfma_f32_16x16x32_bf16 v[2:5], v[134:137], v[190:193], v[2:5]
	v_mfma_f32_16x16x32_bf16 v[6:9], v[142:145], v[190:193], v[6:9]
	v_mfma_f32_16x16x32_bf16 v[14:17], v[150:153], v[190:193], v[14:17]
	v_mfma_f32_16x16x32_bf16 v[10:13], v[158:161], v[190:193], v[10:13]
	v_mfma_f32_16x16x32_bf16 v[18:21], v[158:161], v[198:201], v[18:21]
	v_mfma_f32_16x16x32_bf16 v[22:25], v[150:153], v[198:201], v[22:25]
	v_mfma_f32_16x16x32_bf16 v[26:29], v[142:145], v[198:201], v[26:29]
	v_mfma_f32_16x16x32_bf16 v[30:33], v[134:137], v[198:201], v[30:33]
	v_mfma_f32_16x16x32_bf16 v[34:37], v[134:137], v[210:213], v[34:37]
	v_mfma_f32_16x16x32_bf16 v[42:45], v[142:145], v[210:213], v[42:45]
	v_mfma_f32_16x16x32_bf16 v[46:49], v[150:153], v[210:213], v[46:49]
	v_mfma_f32_16x16x32_bf16 v[38:41], v[158:161], v[210:213], v[38:41]
	v_mfma_f32_16x16x32_bf16 v[50:53], v[158:161], v[238:241], v[50:53]
	v_mfma_f32_16x16x32_bf16 v[54:57], v[150:153], v[238:241], v[54:57]
	v_mfma_f32_16x16x32_bf16 v[58:61], v[142:145], v[238:241], v[58:61]
	v_mfma_f32_16x16x32_bf16 v[62:65], v[134:137], v[238:241], v[62:65]
	s_setprio 0
	s_barrier
	s_add_i32 s68, s82, s41
	v_lshl_add_u64 v[218:219], v[218:219], 0, s[76:77]
	s_mov_b32 m0, s68
	ds_read_b128 v[186:189], v204 offset:49152
	ds_read_b128 v[190:193], v204 offset:50176
	ds_read_b128 v[194:197], v204 offset:51200
	ds_read_b128 v[198:201], v204 offset:52224
	ds_read_b128 v[206:209], v204 offset:53248
	ds_read_b128 v[210:213], v204 offset:54272
	ds_read_b128 v[214:217], v204 offset:55296
	ds_read_b128 v[238:241], v204 offset:56320
	global_load_lds_dwordx4 v[218:219], off
	s_add_i32 m0, s68, 0x2000
	s_add_u32 s6, s6, 0x40080
	v_lshl_add_u64 v[218:219], v[230:231], 0, s[76:77]
	s_addc_u32 s7, s7, 0
	s_add_i32 s68, s83, s41
	global_load_lds_dwordx4 v[218:219], off
	v_lshl_add_u64 v[218:219], s[6:7], 0, v[164:165]
	s_mov_b32 m0, s68
	s_nop 0
	global_load_lds_dwordx4 v[218:219], off
	v_lshl_add_u64 v[218:219], s[6:7], 0, v[162:163]
	s_add_i32 m0, s68, 0x2000
	s_nop 0
	global_load_lds_dwordx4 v[218:219], off
	v_lshl_add_u64 v[218:219], v[232:233], 0, s[76:77]
	s_mov_b32 m0, s34
	s_nop 0
	global_load_lds_dwordx4 v[218:219], off
	v_lshl_add_u64 v[218:219], v[242:243], 0, s[76:77]
	s_mov_b32 m0, s30
	s_nop 0
	global_load_lds_dwordx4 v[218:219], off
	s_waitcnt vmcnt(8)
	s_waitcnt lgkmcnt(0)
	s_barrier
	s_setprio 1
	s_waitcnt lgkmcnt(0)
	v_mfma_f32_16x16x32_bf16 v[74:77], v[130:133], v[186:189], v[74:77]
	v_mfma_f32_16x16x32_bf16 v[70:73], v[138:141], v[186:189], v[70:73]
	v_mfma_f32_16x16x32_bf16 v[78:81], v[146:149], v[186:189], v[78:81]
	v_mfma_f32_16x16x32_bf16 v[66:69], v[154:157], v[186:189], v[66:69]
	v_mfma_f32_16x16x32_bf16 v[82:85], v[154:157], v[194:197], v[82:85]
	v_mfma_f32_16x16x32_bf16 v[86:89], v[146:149], v[194:197], v[86:89]
	v_mfma_f32_16x16x32_bf16 v[90:93], v[138:141], v[194:197], v[90:93]
	v_mfma_f32_16x16x32_bf16 v[94:97], v[130:133], v[194:197], v[94:97]
	v_mfma_f32_16x16x32_bf16 v[106:109], v[130:133], v[206:209], v[106:109]
	v_mfma_f32_16x16x32_bf16 v[102:105], v[138:141], v[206:209], v[102:105]
	v_mfma_f32_16x16x32_bf16 v[110:113], v[146:149], v[206:209], v[110:113]
	v_mfma_f32_16x16x32_bf16 v[98:101], v[154:157], v[206:209], v[98:101]
	v_mfma_f32_16x16x32_bf16 v[126:129], v[154:157], v[214:217], v[126:129]
	v_mfma_f32_16x16x32_bf16 v[122:125], v[146:149], v[214:217], v[122:125]
	v_mfma_f32_16x16x32_bf16 v[114:117], v[138:141], v[214:217], v[114:117]
	v_mfma_f32_16x16x32_bf16 v[118:121], v[130:133], v[214:217], v[118:121]
	s_setprio 0
	s_setprio 1
	v_mfma_f32_16x16x32_bf16 v[74:77], v[134:137], v[190:193], v[74:77]
	v_mfma_f32_16x16x32_bf16 v[70:73], v[142:145], v[190:193], v[70:73]
	v_mfma_f32_16x16x32_bf16 v[78:81], v[150:153], v[190:193], v[78:81]
	v_mfma_f32_16x16x32_bf16 v[66:69], v[158:161], v[190:193], v[66:69]
	v_mfma_f32_16x16x32_bf16 v[82:85], v[158:161], v[198:201], v[82:85]
	v_mfma_f32_16x16x32_bf16 v[86:89], v[150:153], v[198:201], v[86:89]
	v_mfma_f32_16x16x32_bf16 v[90:93], v[142:145], v[198:201], v[90:93]
	v_mfma_f32_16x16x32_bf16 v[94:97], v[134:137], v[198:201], v[94:97]
	v_mfma_f32_16x16x32_bf16 v[106:109], v[134:137], v[210:213], v[106:109]
	v_mfma_f32_16x16x32_bf16 v[102:105], v[142:145], v[210:213], v[102:105]
	v_mfma_f32_16x16x32_bf16 v[110:113], v[150:153], v[210:213], v[110:113]
	v_mfma_f32_16x16x32_bf16 v[98:101], v[158:161], v[210:213], v[98:101]
	v_mfma_f32_16x16x32_bf16 v[126:129], v[158:161], v[238:241], v[126:129]
	v_mfma_f32_16x16x32_bf16 v[122:125], v[150:153], v[238:241], v[122:125]
	v_mfma_f32_16x16x32_bf16 v[114:117], v[142:145], v[238:241], v[114:117]
	v_mfma_f32_16x16x32_bf16 v[118:121], v[134:137], v[238:241], v[118:121]
	s_setprio 0
	s_barrier
	s_add_i32 s59, s59, 2
	s_add_u32 s4, s4, 0x100
	s_addc_u32 s5, s5, 0
	s_add_u32 s46, s46, 0x100
	s_addc_u32 s57, s57, 0
	s_cmp_gt_u32 s59, 13
	s_cbranch_scc0 .LBB0_283
	s_and_b64 vcc, exec, s[42:43]
	s_cbranch_vccz .LBB0_286
	s_barrier

.LBB0_670:
	s_add_u32 s6, s58, 0x80
	s_addc_u32 s7, s59, 0
	s_add_u32 s21, s56, 0x100
	s_addc_u32 s26, s57, 0
	s_mov_b32 s27, 0
	s_add_i32 s46, s27, 2
	s_add_u32 s0, s6, 0x80
	s_addc_u32 s56, s7, 0
	s_add_i32 vcc_lo, 0, 0x10000
	s_cmp_eq_u32 s72, s27
	s_cselect_b32 s57, s51, s56
	s_cselect_b32 s56, s50, s0
	s_cselect_b32 s59, s53, s26
	s_cselect_b32 s58, s52, s21
	s_add_i32 s0, 0, 0x14000
	v_add_u32_e32 v70, vcc_lo, v237
	v_add_u32_e32 v94, s0, v237
	ds_read_b128 v[58:61], v70
	ds_read_b128 v[62:65], v70 offset:1024
	ds_read_b128 v[66:69], v70 offset:2048
	ds_read_b128 v[70:73], v70 offset:3072
	ds_read_b128 v[82:85], v94
	ds_read_b128 v[86:89], v94 offset:1024
	ds_read_b128 v[90:93], v94 offset:2048
	ds_read_b128 v[94:97], v94 offset:3072
	v_lshl_add_u64 v[210:211], s[6:7], 0, v[194:195]
	s_add_i32 m0, s64, 0xc000
	ds_read_b128 v[162:165], v239
	ds_read_b128 v[166:169], v239 offset:1024
	ds_read_b128 v[170:173], v239 offset:2048
	ds_read_b128 v[174:177], v239 offset:3072
	ds_read_b128 v[178:181], v239 offset:4096
	ds_read_b128 v[198:201], v239 offset:5120
	ds_read_b128 v[202:205], v239 offset:6144
	ds_read_b128 v[206:209], v239 offset:7168
	global_load_lds_dwordx4 v[210:211], off
	v_lshl_add_u64 v[210:211], s[6:7], 0, v[196:197]
	s_add_i32 m0, s64, 0xe000
	s_nop 0
	global_load_lds_dwordx4 v[210:211], off
	s_waitcnt vmcnt(8)
	s_waitcnt lgkmcnt(0)
	s_barrier
	s_setprio 1
	s_waitcnt lgkmcnt(0)
	v_mfma_f32_16x16x32_bf16 v[158:161], v[58:61], v[162:165], 0
	v_mfma_f32_16x16x32_bf16 v[154:157], v[66:69], v[162:165], 0
	v_mfma_f32_16x16x32_bf16 v[150:153], v[82:85], v[162:165], 0
	v_mfma_f32_16x16x32_bf16 v[146:149], v[90:93], v[162:165], 0
	v_mfma_f32_16x16x32_bf16 v[130:133], v[90:93], v[170:173], 0
	v_mfma_f32_16x16x32_bf16 v[134:137], v[82:85], v[170:173], 0
	v_mfma_f32_16x16x32_bf16 v[138:141], v[66:69], v[170:173], 0
	v_mfma_f32_16x16x32_bf16 v[142:145], v[58:61], v[170:173], 0
	v_mfma_f32_16x16x32_bf16 v[126:129], v[58:61], v[178:181], 0
	v_mfma_f32_16x16x32_bf16 v[122:125], v[66:69], v[178:181], 0
	v_mfma_f32_16x16x32_bf16 v[118:121], v[82:85], v[178:181], 0
	v_mfma_f32_16x16x32_bf16 v[114:117], v[90:93], v[178:181], 0
	v_mfma_f32_16x16x32_bf16 v[98:101], v[90:93], v[202:205], 0
	v_mfma_f32_16x16x32_bf16 v[102:105], v[82:85], v[202:205], 0
	v_mfma_f32_16x16x32_bf16 v[106:109], v[66:69], v[202:205], 0
	v_mfma_f32_16x16x32_bf16 v[110:113], v[58:61], v[202:205], 0
	s_setprio 0
	s_setprio 1
	v_mfma_f32_16x16x32_bf16 v[158:161], v[62:65], v[166:169], v[158:161]
	v_mfma_f32_16x16x32_bf16 v[154:157], v[70:73], v[166:169], v[154:157]
	v_mfma_f32_16x16x32_bf16 v[150:153], v[86:89], v[166:169], v[150:153]
	v_mfma_f32_16x16x32_bf16 v[146:149], v[94:97], v[166:169], v[146:149]
	v_mfma_f32_16x16x32_bf16 v[130:133], v[94:97], v[174:177], v[130:133]
	v_mfma_f32_16x16x32_bf16 v[134:137], v[86:89], v[174:177], v[134:137]
	v_mfma_f32_16x16x32_bf16 v[138:141], v[70:73], v[174:177], v[138:141]
	v_mfma_f32_16x16x32_bf16 v[142:145], v[62:65], v[174:177], v[142:145]
	v_mfma_f32_16x16x32_bf16 v[126:129], v[62:65], v[198:201], v[126:129]
	v_mfma_f32_16x16x32_bf16 v[122:125], v[70:73], v[198:201], v[122:125]
	v_mfma_f32_16x16x32_bf16 v[118:121], v[86:89], v[198:201], v[118:121]
	v_mfma_f32_16x16x32_bf16 v[114:117], v[94:97], v[198:201], v[114:117]
	v_mfma_f32_16x16x32_bf16 v[98:101], v[94:97], v[206:209], v[98:101]
	v_mfma_f32_16x16x32_bf16 v[102:105], v[86:89], v[206:209], v[102:105]
	v_mfma_f32_16x16x32_bf16 v[106:109], v[70:73], v[206:209], v[106:109]
	v_mfma_f32_16x16x32_bf16 v[110:113], v[62:65], v[206:209], v[110:113]
	s_setprio 0
	s_barrier
	s_add_i32 s27, vcc_lo, s61
	v_lshl_add_u64 v[210:211], s[58:59], 0, v[186:187]
	s_mov_b32 m0, s27
	ds_read_b128 v[162:165], v239 offset:16384
	ds_read_b128 v[166:169], v239 offset:17408
	ds_read_b128 v[170:173], v239 offset:18432
	ds_read_b128 v[174:177], v239 offset:19456
	ds_read_b128 v[178:181], v239 offset:20480
	ds_read_b128 v[198:201], v239 offset:21504
	ds_read_b128 v[202:205], v239 offset:22528
	ds_read_b128 v[206:209], v239 offset:23552
	global_load_lds_dwordx4 v[210:211], off
	s_add_i32 m0, s27, 0x2000
	v_lshl_add_u64 v[212:213], s[58:59], 0, v[182:183]
	s_add_u32 s58, s58, s12
	s_addc_u32 s59, s59, 0
	s_add_i32 s0, s0, s61
	global_load_lds_dwordx4 v[212:213], off
	v_lshl_add_u64 v[214:215], s[58:59], 0, v[186:187]
	s_mov_b32 m0, s0
	v_lshl_add_u64 v[216:217], s[58:59], 0, v[182:183]
	global_load_lds_dwordx4 v[214:215], off
	s_add_i32 m0, s0, 0x2000
	v_lshl_add_u64 v[218:219], s[56:57], 0, v[188:189]
	global_load_lds_dwordx4 v[216:217], off
	s_mov_b32 m0, s64
	v_lshl_add_u64 v[230:231], s[56:57], 0, v[184:185]
	global_load_lds_dwordx4 v[218:219], off
	s_mov_b32 m0, s65
	s_nop 0
	global_load_lds_dwordx4 v[230:231], off
	s_waitcnt vmcnt(8)
	s_waitcnt lgkmcnt(0)
	s_barrier
	s_setprio 1
	s_waitcnt lgkmcnt(0)
	v_mfma_f32_16x16x32_bf16 v[78:81], v[58:61], v[162:165], 0
	v_mfma_f32_16x16x32_bf16 v[74:77], v[66:69], v[162:165], 0
	v_mfma_f32_16x16x32_bf16 v[54:57], v[82:85], v[162:165], 0
	v_mfma_f32_16x16x32_bf16 v[50:53], v[90:93], v[162:165], 0
	v_mfma_f32_16x16x32_bf16 v[34:37], v[90:93], v[170:173], 0
	v_mfma_f32_16x16x32_bf16 v[38:41], v[82:85], v[170:173], 0
	v_mfma_f32_16x16x32_bf16 v[42:45], v[66:69], v[170:173], 0
	v_mfma_f32_16x16x32_bf16 v[46:49], v[58:61], v[170:173], 0
	v_mfma_f32_16x16x32_bf16 v[30:33], v[58:61], v[178:181], 0
	v_mfma_f32_16x16x32_bf16 v[26:29], v[66:69], v[178:181], 0
	v_mfma_f32_16x16x32_bf16 v[22:25], v[82:85], v[178:181], 0
	v_mfma_f32_16x16x32_bf16 v[18:21], v[90:93], v[178:181], 0
	v_mfma_f32_16x16x32_bf16 v[2:5], v[90:93], v[202:205], 0
	v_mfma_f32_16x16x32_bf16 v[6:9], v[82:85], v[202:205], 0
	v_mfma_f32_16x16x32_bf16 v[10:13], v[66:69], v[202:205], 0
	v_mfma_f32_16x16x32_bf16 v[14:17], v[58:61], v[202:205], 0
	s_setprio 0
	s_setprio 1
	v_mfma_f32_16x16x32_bf16 v[78:81], v[62:65], v[166:169], v[78:81]
	v_mfma_f32_16x16x32_bf16 v[74:77], v[70:73], v[166:169], v[74:77]
	v_mfma_f32_16x16x32_bf16 v[54:57], v[86:89], v[166:169], v[54:57]
	v_mfma_f32_16x16x32_bf16 v[50:53], v[94:97], v[166:169], v[50:53]
	v_mfma_f32_16x16x32_bf16 v[34:37], v[94:97], v[174:177], v[34:37]
	v_mfma_f32_16x16x32_bf16 v[38:41], v[86:89], v[174:177], v[38:41]
	v_mfma_f32_16x16x32_bf16 v[42:45], v[70:73], v[174:177], v[42:45]
	v_mfma_f32_16x16x32_bf16 v[46:49], v[62:65], v[174:177], v[46:49]
	v_mfma_f32_16x16x32_bf16 v[30:33], v[62:65], v[198:201], v[30:33]
	v_mfma_f32_16x16x32_bf16 v[26:29], v[70:73], v[198:201], v[26:29]
	v_mfma_f32_16x16x32_bf16 v[22:25], v[86:89], v[198:201], v[22:25]
	v_mfma_f32_16x16x32_bf16 v[18:21], v[94:97], v[198:201], v[18:21]
	v_mfma_f32_16x16x32_bf16 v[2:5], v[94:97], v[206:209], v[2:5]
	v_mfma_f32_16x16x32_bf16 v[6:9], v[86:89], v[206:209], v[6:9]
	v_mfma_f32_16x16x32_bf16 v[10:13], v[70:73], v[206:209], v[10:13]
	v_mfma_f32_16x16x32_bf16 v[14:17], v[62:65], v[206:209], v[14:17]
	s_setprio 0
	s_barrier
	s_add_i32 s0, 0, 0x18000
	s_add_i32 s27, 0, 0x1c000
	v_add_u32_e32 v70, s0, v237
	v_add_u32_e32 v94, s27, v237
	ds_read_b128 v[58:61], v70
	ds_read_b128 v[62:65], v70 offset:1024
	ds_read_b128 v[66:69], v70 offset:2048
	ds_read_b128 v[70:73], v70 offset:3072
	ds_read_b128 v[82:85], v94
	ds_read_b128 v[86:89], v94 offset:1024
	ds_read_b128 v[90:93], v94 offset:2048
	ds_read_b128 v[94:97], v94 offset:3072
	s_add_u32 s56, s56, s12
	s_addc_u32 s57, s57, 0
	s_mov_b32 m0, s66
	v_lshl_add_u64 v[232:233], s[56:57], 0, v[188:189]
	ds_read_b128 v[162:165], v239 offset:32768
	ds_read_b128 v[166:169], v239 offset:33792
	ds_read_b128 v[170:173], v239 offset:34816
	ds_read_b128 v[174:177], v239 offset:35840
	ds_read_b128 v[178:181], v239 offset:36864
	ds_read_b128 v[198:201], v239 offset:37888
	ds_read_b128 v[202:205], v239 offset:38912
	ds_read_b128 v[206:209], v239 offset:39936
	global_load_lds_dwordx4 v[232:233], off
	v_lshl_add_u64 v[232:233], s[56:57], 0, v[184:185]
	s_mov_b32 m0, s67
	s_nop 0
	global_load_lds_dwordx4 v[232:233], off
	s_waitcnt vmcnt(8)
	s_waitcnt lgkmcnt(0)
	s_barrier
	s_setprio 1
	s_waitcnt lgkmcnt(0)
	v_mfma_f32_16x16x32_bf16 v[158:161], v[58:61], v[162:165], v[158:161]
	v_mfma_f32_16x16x32_bf16 v[154:157], v[66:69], v[162:165], v[154:157]
	v_mfma_f32_16x16x32_bf16 v[150:153], v[82:85], v[162:165], v[150:153]
	v_mfma_f32_16x16x32_bf16 v[146:149], v[90:93], v[162:165], v[146:149]
	v_mfma_f32_16x16x32_bf16 v[130:133], v[90:93], v[170:173], v[130:133]
	v_mfma_f32_16x16x32_bf16 v[134:137], v[82:85], v[170:173], v[134:137]
	v_mfma_f32_16x16x32_bf16 v[138:141], v[66:69], v[170:173], v[138:141]
	v_mfma_f32_16x16x32_bf16 v[142:145], v[58:61], v[170:173], v[142:145]
	v_mfma_f32_16x16x32_bf16 v[126:129], v[58:61], v[178:181], v[126:129]
	v_mfma_f32_16x16x32_bf16 v[122:125], v[66:69], v[178:181], v[122:125]
	v_mfma_f32_16x16x32_bf16 v[118:121], v[82:85], v[178:181], v[118:121]
	v_mfma_f32_16x16x32_bf16 v[114:117], v[90:93], v[178:181], v[114:117]
	v_mfma_f32_16x16x32_bf16 v[98:101], v[90:93], v[202:205], v[98:101]
	v_mfma_f32_16x16x32_bf16 v[102:105], v[82:85], v[202:205], v[102:105]
	v_mfma_f32_16x16x32_bf16 v[106:109], v[66:69], v[202:205], v[106:109]
	v_mfma_f32_16x16x32_bf16 v[110:113], v[58:61], v[202:205], v[110:113]
	s_setprio 0
	s_setprio 1
	v_mfma_f32_16x16x32_bf16 v[158:161], v[62:65], v[166:169], v[158:161]
	v_mfma_f32_16x16x32_bf16 v[154:157], v[70:73], v[166:169], v[154:157]
	v_mfma_f32_16x16x32_bf16 v[150:153], v[86:89], v[166:169], v[150:153]
	v_mfma_f32_16x16x32_bf16 v[146:149], v[94:97], v[166:169], v[146:149]
	v_mfma_f32_16x16x32_bf16 v[130:133], v[94:97], v[174:177], v[130:133]
	v_mfma_f32_16x16x32_bf16 v[134:137], v[86:89], v[174:177], v[134:137]
	v_mfma_f32_16x16x32_bf16 v[138:141], v[70:73], v[174:177], v[138:141]
	v_mfma_f32_16x16x32_bf16 v[142:145], v[62:65], v[174:177], v[142:145]
	v_mfma_f32_16x16x32_bf16 v[126:129], v[62:65], v[198:201], v[126:129]
	v_mfma_f32_16x16x32_bf16 v[122:125], v[70:73], v[198:201], v[122:125]
	v_mfma_f32_16x16x32_bf16 v[118:121], v[86:89], v[198:201], v[118:121]
	v_mfma_f32_16x16x32_bf16 v[114:117], v[94:97], v[198:201], v[114:117]
	v_mfma_f32_16x16x32_bf16 v[98:101], v[94:97], v[206:209], v[98:101]
	v_mfma_f32_16x16x32_bf16 v[102:105], v[86:89], v[206:209], v[102:105]
	v_mfma_f32_16x16x32_bf16 v[106:109], v[70:73], v[206:209], v[106:109]
	v_mfma_f32_16x16x32_bf16 v[110:113], v[62:65], v[206:209], v[110:113]
	s_setprio 0
	s_barrier
	s_add_i32 s0, s0, s61
	v_lshl_add_u64 v[210:211], v[210:211], 0, s[76:77]
	s_mov_b32 m0, s0
	ds_read_b128 v[162:165], v239 offset:49152
	ds_read_b128 v[166:169], v239 offset:50176
	ds_read_b128 v[170:173], v239 offset:51200
	ds_read_b128 v[174:177], v239 offset:52224
	ds_read_b128 v[178:181], v239 offset:53248
	ds_read_b128 v[198:201], v239 offset:54272
	ds_read_b128 v[202:205], v239 offset:55296
	ds_read_b128 v[206:209], v239 offset:56320
	global_load_lds_dwordx4 v[210:211], off
	v_lshl_add_u64 v[210:211], v[212:213], 0, s[76:77]
	s_add_i32 m0, s0, 0x2000
	s_add_i32 s0, s27, s61
	global_load_lds_dwordx4 v[210:211], off
	v_lshl_add_u64 v[210:211], v[214:215], 0, s[76:77]
	s_mov_b32 m0, s0
	s_nop 0
	global_load_lds_dwordx4 v[210:211], off
	v_lshl_add_u64 v[210:211], v[216:217], 0, s[76:77]
	s_add_i32 m0, s0, 0x2000
	s_nop 0
	global_load_lds_dwordx4 v[210:211], off
	v_lshl_add_u64 v[210:211], v[218:219], 0, s[76:77]
	s_mov_b32 m0, s68
	s_nop 0
	global_load_lds_dwordx4 v[210:211], off
	v_lshl_add_u64 v[210:211], v[230:231], 0, s[76:77]
	s_mov_b32 m0, s69
	s_nop 0
	global_load_lds_dwordx4 v[210:211], off
	s_waitcnt vmcnt(8)
	s_waitcnt lgkmcnt(0)
	s_barrier
	s_setprio 1
	s_waitcnt lgkmcnt(0)
	v_mfma_f32_16x16x32_bf16 v[78:81], v[58:61], v[162:165], v[78:81]
	v_mfma_f32_16x16x32_bf16 v[74:77], v[66:69], v[162:165], v[74:77]
	v_mfma_f32_16x16x32_bf16 v[54:57], v[82:85], v[162:165], v[54:57]
	v_mfma_f32_16x16x32_bf16 v[50:53], v[90:93], v[162:165], v[50:53]
	v_mfma_f32_16x16x32_bf16 v[34:37], v[90:93], v[170:173], v[34:37]
	v_mfma_f32_16x16x32_bf16 v[38:41], v[82:85], v[170:173], v[38:41]
	v_mfma_f32_16x16x32_bf16 v[42:45], v[66:69], v[170:173], v[42:45]
	v_mfma_f32_16x16x32_bf16 v[46:49], v[58:61], v[170:173], v[46:49]
	v_mfma_f32_16x16x32_bf16 v[30:33], v[58:61], v[178:181], v[30:33]
	v_mfma_f32_16x16x32_bf16 v[26:29], v[66:69], v[178:181], v[26:29]
	v_mfma_f32_16x16x32_bf16 v[22:25], v[82:85], v[178:181], v[22:25]
	v_mfma_f32_16x16x32_bf16 v[18:21], v[90:93], v[178:181], v[18:21]
	v_mfma_f32_16x16x32_bf16 v[2:5], v[90:93], v[202:205], v[2:5]
	v_mfma_f32_16x16x32_bf16 v[6:9], v[82:85], v[202:205], v[6:9]
	v_mfma_f32_16x16x32_bf16 v[10:13], v[66:69], v[202:205], v[10:13]
	v_mfma_f32_16x16x32_bf16 v[14:17], v[58:61], v[202:205], v[14:17]
	s_setprio 0
	s_setprio 1
	v_mfma_f32_16x16x32_bf16 v[78:81], v[62:65], v[166:169], v[78:81]
	v_mfma_f32_16x16x32_bf16 v[74:77], v[70:73], v[166:169], v[74:77]
	v_mfma_f32_16x16x32_bf16 v[54:57], v[86:89], v[166:169], v[54:57]
	v_mfma_f32_16x16x32_bf16 v[50:53], v[94:97], v[166:169], v[50:53]
	v_mfma_f32_16x16x32_bf16 v[34:37], v[94:97], v[174:177], v[34:37]
	v_mfma_f32_16x16x32_bf16 v[38:41], v[86:89], v[174:177], v[38:41]
	v_mfma_f32_16x16x32_bf16 v[42:45], v[70:73], v[174:177], v[42:45]
	v_mfma_f32_16x16x32_bf16 v[46:49], v[62:65], v[174:177], v[46:49]
	v_mfma_f32_16x16x32_bf16 v[30:33], v[62:65], v[198:201], v[30:33]
	v_mfma_f32_16x16x32_bf16 v[26:29], v[70:73], v[198:201], v[26:29]
	v_mfma_f32_16x16x32_bf16 v[22:25], v[86:89], v[198:201], v[22:25]
	v_mfma_f32_16x16x32_bf16 v[18:21], v[94:97], v[198:201], v[18:21]
	v_mfma_f32_16x16x32_bf16 v[2:5], v[94:97], v[206:209], v[2:5]
	v_mfma_f32_16x16x32_bf16 v[6:9], v[86:89], v[206:209], v[6:9]
	v_mfma_f32_16x16x32_bf16 v[10:13], v[70:73], v[206:209], v[10:13]
	v_mfma_f32_16x16x32_bf16 v[14:17], v[62:65], v[206:209], v[14:17]
	s_setprio 0
	s_barrier
	s_add_u32 s6, s6, 0x100
	s_addc_u32 s7, s7, 0
	s_add_u32 s21, s21, 0x100
	s_addc_u32 s26, s26, 0
	s_mov_b32 s27, s46
.LBB0_671:
	s_add_i32 s46, s27, 2
	s_add_u32 s0, s6, 0x80
	s_addc_u32 s56, s7, 0
	s_add_i32 vcc_lo, 0, 0x10000
	s_cmp_eq_u32 s72, s27
	s_cselect_b32 s57, s51, s56
	s_cselect_b32 s56, s50, s0
	s_cselect_b32 s59, s53, s26
	s_cselect_b32 s58, s52, s21
	s_add_i32 s0, 0, 0x14000
	v_add_u32_e32 v70, vcc_lo, v237
	v_add_u32_e32 v94, s0, v237
	ds_read_b128 v[58:61], v70
	ds_read_b128 v[62:65], v70 offset:1024
	ds_read_b128 v[66:69], v70 offset:2048
	ds_read_b128 v[70:73], v70 offset:3072
	ds_read_b128 v[82:85], v94
	ds_read_b128 v[86:89], v94 offset:1024
	ds_read_b128 v[90:93], v94 offset:2048
	ds_read_b128 v[94:97], v94 offset:3072
	v_lshl_add_u64 v[210:211], s[6:7], 0, v[194:195]
	s_add_i32 m0, s64, 0xc000
	ds_read_b128 v[162:165], v239
	ds_read_b128 v[166:169], v239 offset:1024
	ds_read_b128 v[170:173], v239 offset:2048
	ds_read_b128 v[174:177], v239 offset:3072
	ds_read_b128 v[178:181], v239 offset:4096
	ds_read_b128 v[198:201], v239 offset:5120
	ds_read_b128 v[202:205], v239 offset:6144
	ds_read_b128 v[206:209], v239 offset:7168
	global_load_lds_dwordx4 v[210:211], off
	v_lshl_add_u64 v[210:211], s[6:7], 0, v[196:197]
	s_add_i32 m0, s64, 0xe000
	s_nop 0
	global_load_lds_dwordx4 v[210:211], off
	s_waitcnt vmcnt(8)
	s_waitcnt lgkmcnt(0)
	s_barrier
	s_setprio 1
	s_waitcnt lgkmcnt(0)
	v_mfma_f32_16x16x32_bf16 v[158:161], v[58:61], v[162:165], v[158:161]
	v_mfma_f32_16x16x32_bf16 v[154:157], v[66:69], v[162:165], v[154:157]
	v_mfma_f32_16x16x32_bf16 v[150:153], v[82:85], v[162:165], v[150:153]
	v_mfma_f32_16x16x32_bf16 v[146:149], v[90:93], v[162:165], v[146:149]
	v_mfma_f32_16x16x32_bf16 v[130:133], v[90:93], v[170:173], v[130:133]
	v_mfma_f32_16x16x32_bf16 v[134:137], v[82:85], v[170:173], v[134:137]
	v_mfma_f32_16x16x32_bf16 v[138:141], v[66:69], v[170:173], v[138:141]
	v_mfma_f32_16x16x32_bf16 v[142:145], v[58:61], v[170:173], v[142:145]
	v_mfma_f32_16x16x32_bf16 v[126:129], v[58:61], v[178:181], v[126:129]
	v_mfma_f32_16x16x32_bf16 v[122:125], v[66:69], v[178:181], v[122:125]
	v_mfma_f32_16x16x32_bf16 v[118:121], v[82:85], v[178:181], v[118:121]
	v_mfma_f32_16x16x32_bf16 v[114:117], v[90:93], v[178:181], v[114:117]
	v_mfma_f32_16x16x32_bf16 v[98:101], v[90:93], v[202:205], v[98:101]
	v_mfma_f32_16x16x32_bf16 v[102:105], v[82:85], v[202:205], v[102:105]
	v_mfma_f32_16x16x32_bf16 v[106:109], v[66:69], v[202:205], v[106:109]
	v_mfma_f32_16x16x32_bf16 v[110:113], v[58:61], v[202:205], v[110:113]
	s_setprio 0
	s_setprio 1
	v_mfma_f32_16x16x32_bf16 v[158:161], v[62:65], v[166:169], v[158:161]
	v_mfma_f32_16x16x32_bf16 v[154:157], v[70:73], v[166:169], v[154:157]
	v_mfma_f32_16x16x32_bf16 v[150:153], v[86:89], v[166:169], v[150:153]
	v_mfma_f32_16x16x32_bf16 v[146:149], v[94:97], v[166:169], v[146:149]
	v_mfma_f32_16x16x32_bf16 v[130:133], v[94:97], v[174:177], v[130:133]
	v_mfma_f32_16x16x32_bf16 v[134:137], v[86:89], v[174:177], v[134:137]
	v_mfma_f32_16x16x32_bf16 v[138:141], v[70:73], v[174:177], v[138:141]
	v_mfma_f32_16x16x32_bf16 v[142:145], v[62:65], v[174:177], v[142:145]
	v_mfma_f32_16x16x32_bf16 v[126:129], v[62:65], v[198:201], v[126:129]
	v_mfma_f32_16x16x32_bf16 v[122:125], v[70:73], v[198:201], v[122:125]
	v_mfma_f32_16x16x32_bf16 v[118:121], v[86:89], v[198:201], v[118:121]
	v_mfma_f32_16x16x32_bf16 v[114:117], v[94:97], v[198:201], v[114:117]
	v_mfma_f32_16x16x32_bf16 v[98:101], v[94:97], v[206:209], v[98:101]
	v_mfma_f32_16x16x32_bf16 v[102:105], v[86:89], v[206:209], v[102:105]
	v_mfma_f32_16x16x32_bf16 v[106:109], v[70:73], v[206:209], v[106:109]
	v_mfma_f32_16x16x32_bf16 v[110:113], v[62:65], v[206:209], v[110:113]
	s_setprio 0
	s_barrier
	s_add_i32 s27, vcc_lo, s61
	v_lshl_add_u64 v[210:211], s[58:59], 0, v[186:187]
	s_mov_b32 m0, s27
	ds_read_b128 v[162:165], v239 offset:16384
	ds_read_b128 v[166:169], v239 offset:17408
	ds_read_b128 v[170:173], v239 offset:18432
	ds_read_b128 v[174:177], v239 offset:19456
	ds_read_b128 v[178:181], v239 offset:20480
	ds_read_b128 v[198:201], v239 offset:21504
	ds_read_b128 v[202:205], v239 offset:22528
	ds_read_b128 v[206:209], v239 offset:23552
	global_load_lds_dwordx4 v[210:211], off
	s_add_i32 m0, s27, 0x2000
	v_lshl_add_u64 v[212:213], s[58:59], 0, v[182:183]
	s_add_u32 s58, s58, s12
	s_addc_u32 s59, s59, 0
	s_add_i32 s0, s0, s61
	global_load_lds_dwordx4 v[212:213], off
	v_lshl_add_u64 v[214:215], s[58:59], 0, v[186:187]
	s_mov_b32 m0, s0
	v_lshl_add_u64 v[216:217], s[58:59], 0, v[182:183]
	global_load_lds_dwordx4 v[214:215], off
	s_add_i32 m0, s0, 0x2000
	v_lshl_add_u64 v[218:219], s[56:57], 0, v[188:189]
	global_load_lds_dwordx4 v[216:217], off
	s_mov_b32 m0, s64
	v_lshl_add_u64 v[230:231], s[56:57], 0, v[184:185]
	global_load_lds_dwordx4 v[218:219], off
	s_mov_b32 m0, s65
	s_nop 0
	global_load_lds_dwordx4 v[230:231], off
	s_waitcnt vmcnt(8)
	s_waitcnt lgkmcnt(0)
	s_barrier
	s_setprio 1
	s_waitcnt lgkmcnt(0)
	v_mfma_f32_16x16x32_bf16 v[78:81], v[58:61], v[162:165], v[78:81]
	v_mfma_f32_16x16x32_bf16 v[74:77], v[66:69], v[162:165], v[74:77]
	v_mfma_f32_16x16x32_bf16 v[54:57], v[82:85], v[162:165], v[54:57]
	v_mfma_f32_16x16x32_bf16 v[50:53], v[90:93], v[162:165], v[50:53]
	v_mfma_f32_16x16x32_bf16 v[34:37], v[90:93], v[170:173], v[34:37]
	v_mfma_f32_16x16x32_bf16 v[38:41], v[82:85], v[170:173], v[38:41]
	v_mfma_f32_16x16x32_bf16 v[42:45], v[66:69], v[170:173], v[42:45]
	v_mfma_f32_16x16x32_bf16 v[46:49], v[58:61], v[170:173], v[46:49]
	v_mfma_f32_16x16x32_bf16 v[30:33], v[58:61], v[178:181], v[30:33]
	v_mfma_f32_16x16x32_bf16 v[26:29], v[66:69], v[178:181], v[26:29]
	v_mfma_f32_16x16x32_bf16 v[22:25], v[82:85], v[178:181], v[22:25]
	v_mfma_f32_16x16x32_bf16 v[18:21], v[90:93], v[178:181], v[18:21]
	v_mfma_f32_16x16x32_bf16 v[2:5], v[90:93], v[202:205], v[2:5]
	v_mfma_f32_16x16x32_bf16 v[6:9], v[82:85], v[202:205], v[6:9]
	v_mfma_f32_16x16x32_bf16 v[10:13], v[66:69], v[202:205], v[10:13]
	v_mfma_f32_16x16x32_bf16 v[14:17], v[58:61], v[202:205], v[14:17]
	s_setprio 0
	s_setprio 1
	v_mfma_f32_16x16x32_bf16 v[78:81], v[62:65], v[166:169], v[78:81]
	v_mfma_f32_16x16x32_bf16 v[74:77], v[70:73], v[166:169], v[74:77]
	v_mfma_f32_16x16x32_bf16 v[54:57], v[86:89], v[166:169], v[54:57]
	v_mfma_f32_16x16x32_bf16 v[50:53], v[94:97], v[166:169], v[50:53]
	v_mfma_f32_16x16x32_bf16 v[34:37], v[94:97], v[174:177], v[34:37]
	v_mfma_f32_16x16x32_bf16 v[38:41], v[86:89], v[174:177], v[38:41]
	v_mfma_f32_16x16x32_bf16 v[42:45], v[70:73], v[174:177], v[42:45]
	v_mfma_f32_16x16x32_bf16 v[46:49], v[62:65], v[174:177], v[46:49]
	v_mfma_f32_16x16x32_bf16 v[30:33], v[62:65], v[198:201], v[30:33]
	v_mfma_f32_16x16x32_bf16 v[26:29], v[70:73], v[198:201], v[26:29]
	v_mfma_f32_16x16x32_bf16 v[22:25], v[86:89], v[198:201], v[22:25]
	v_mfma_f32_16x16x32_bf16 v[18:21], v[94:97], v[198:201], v[18:21]
	v_mfma_f32_16x16x32_bf16 v[2:5], v[94:97], v[206:209], v[2:5]
	v_mfma_f32_16x16x32_bf16 v[6:9], v[86:89], v[206:209], v[6:9]
	v_mfma_f32_16x16x32_bf16 v[10:13], v[70:73], v[206:209], v[10:13]
	v_mfma_f32_16x16x32_bf16 v[14:17], v[62:65], v[206:209], v[14:17]
	s_setprio 0
	s_barrier
	s_add_i32 s0, 0, 0x18000
	s_add_i32 s27, 0, 0x1c000
	v_add_u32_e32 v70, s0, v237
	v_add_u32_e32 v94, s27, v237
	ds_read_b128 v[58:61], v70
	ds_read_b128 v[62:65], v70 offset:1024
	ds_read_b128 v[66:69], v70 offset:2048
	ds_read_b128 v[70:73], v70 offset:3072
	ds_read_b128 v[82:85], v94
	ds_read_b128 v[86:89], v94 offset:1024
	ds_read_b128 v[90:93], v94 offset:2048
	ds_read_b128 v[94:97], v94 offset:3072
	s_add_u32 s56, s56, s12
	s_addc_u32 s57, s57, 0
	s_mov_b32 m0, s66
	v_lshl_add_u64 v[232:233], s[56:57], 0, v[188:189]
	ds_read_b128 v[162:165], v239 offset:32768
	ds_read_b128 v[166:169], v239 offset:33792
	ds_read_b128 v[170:173], v239 offset:34816
	ds_read_b128 v[174:177], v239 offset:35840
	ds_read_b128 v[178:181], v239 offset:36864
	ds_read_b128 v[198:201], v239 offset:37888
	ds_read_b128 v[202:205], v239 offset:38912
	ds_read_b128 v[206:209], v239 offset:39936
	global_load_lds_dwordx4 v[232:233], off
	v_lshl_add_u64 v[232:233], s[56:57], 0, v[184:185]
	s_mov_b32 m0, s67
	s_nop 0
	global_load_lds_dwordx4 v[232:233], off
	s_waitcnt vmcnt(8)
	s_waitcnt lgkmcnt(0)
	s_barrier
	s_setprio 1
	s_waitcnt lgkmcnt(0)
	v_mfma_f32_16x16x32_bf16 v[158:161], v[58:61], v[162:165], v[158:161]
	v_mfma_f32_16x16x32_bf16 v[154:157], v[66:69], v[162:165], v[154:157]
	v_mfma_f32_16x16x32_bf16 v[150:153], v[82:85], v[162:165], v[150:153]
	v_mfma_f32_16x16x32_bf16 v[146:149], v[90:93], v[162:165], v[146:149]
	v_mfma_f32_16x16x32_bf16 v[130:133], v[90:93], v[170:173], v[130:133]
	v_mfma_f32_16x16x32_bf16 v[134:137], v[82:85], v[170:173], v[134:137]
	v_mfma_f32_16x16x32_bf16 v[138:141], v[66:69], v[170:173], v[138:141]
	v_mfma_f32_16x16x32_bf16 v[142:145], v[58:61], v[170:173], v[142:145]
	v_mfma_f32_16x16x32_bf16 v[126:129], v[58:61], v[178:181], v[126:129]
	v_mfma_f32_16x16x32_bf16 v[122:125], v[66:69], v[178:181], v[122:125]
	v_mfma_f32_16x16x32_bf16 v[118:121], v[82:85], v[178:181], v[118:121]
	v_mfma_f32_16x16x32_bf16 v[114:117], v[90:93], v[178:181], v[114:117]
	v_mfma_f32_16x16x32_bf16 v[98:101], v[90:93], v[202:205], v[98:101]
	v_mfma_f32_16x16x32_bf16 v[102:105], v[82:85], v[202:205], v[102:105]
	v_mfma_f32_16x16x32_bf16 v[106:109], v[66:69], v[202:205], v[106:109]
	v_mfma_f32_16x16x32_bf16 v[110:113], v[58:61], v[202:205], v[110:113]
	s_setprio 0
	s_setprio 1
	v_mfma_f32_16x16x32_bf16 v[158:161], v[62:65], v[166:169], v[158:161]
	v_mfma_f32_16x16x32_bf16 v[154:157], v[70:73], v[166:169], v[154:157]
	v_mfma_f32_16x16x32_bf16 v[150:153], v[86:89], v[166:169], v[150:153]
	v_mfma_f32_16x16x32_bf16 v[146:149], v[94:97], v[166:169], v[146:149]
	v_mfma_f32_16x16x32_bf16 v[130:133], v[94:97], v[174:177], v[130:133]
	v_mfma_f32_16x16x32_bf16 v[134:137], v[86:89], v[174:177], v[134:137]
	v_mfma_f32_16x16x32_bf16 v[138:141], v[70:73], v[174:177], v[138:141]
	v_mfma_f32_16x16x32_bf16 v[142:145], v[62:65], v[174:177], v[142:145]
	v_mfma_f32_16x16x32_bf16 v[126:129], v[62:65], v[198:201], v[126:129]
	v_mfma_f32_16x16x32_bf16 v[122:125], v[70:73], v[198:201], v[122:125]
	v_mfma_f32_16x16x32_bf16 v[118:121], v[86:89], v[198:201], v[118:121]
	v_mfma_f32_16x16x32_bf16 v[114:117], v[94:97], v[198:201], v[114:117]
	v_mfma_f32_16x16x32_bf16 v[98:101], v[94:97], v[206:209], v[98:101]
	v_mfma_f32_16x16x32_bf16 v[102:105], v[86:89], v[206:209], v[102:105]
	v_mfma_f32_16x16x32_bf16 v[106:109], v[70:73], v[206:209], v[106:109]
	v_mfma_f32_16x16x32_bf16 v[110:113], v[62:65], v[206:209], v[110:113]
	s_setprio 0
	s_barrier
	s_add_i32 s0, s0, s61
	v_lshl_add_u64 v[210:211], v[210:211], 0, s[76:77]
	s_mov_b32 m0, s0
	ds_read_b128 v[162:165], v239 offset:49152
	ds_read_b128 v[166:169], v239 offset:50176
	ds_read_b128 v[170:173], v239 offset:51200
	ds_read_b128 v[174:177], v239 offset:52224
	ds_read_b128 v[178:181], v239 offset:53248
	ds_read_b128 v[198:201], v239 offset:54272
	ds_read_b128 v[202:205], v239 offset:55296
	ds_read_b128 v[206:209], v239 offset:56320
	global_load_lds_dwordx4 v[210:211], off
	v_lshl_add_u64 v[210:211], v[212:213], 0, s[76:77]
	s_add_i32 m0, s0, 0x2000
	s_add_i32 s0, s27, s61
	global_load_lds_dwordx4 v[210:211], off
	v_lshl_add_u64 v[210:211], v[214:215], 0, s[76:77]
	s_mov_b32 m0, s0
	s_nop 0
	global_load_lds_dwordx4 v[210:211], off
	v_lshl_add_u64 v[210:211], v[216:217], 0, s[76:77]
	s_add_i32 m0, s0, 0x2000
	s_nop 0
	global_load_lds_dwordx4 v[210:211], off
	v_lshl_add_u64 v[210:211], v[218:219], 0, s[76:77]
	s_mov_b32 m0, s68
	s_nop 0
	global_load_lds_dwordx4 v[210:211], off
	v_lshl_add_u64 v[210:211], v[230:231], 0, s[76:77]
	s_mov_b32 m0, s69
	s_nop 0
	global_load_lds_dwordx4 v[210:211], off
	s_waitcnt vmcnt(8)
	s_waitcnt lgkmcnt(0)
	s_barrier
	s_setprio 1
	s_waitcnt lgkmcnt(0)
	v_mfma_f32_16x16x32_bf16 v[78:81], v[58:61], v[162:165], v[78:81]
	v_mfma_f32_16x16x32_bf16 v[74:77], v[66:69], v[162:165], v[74:77]
	v_mfma_f32_16x16x32_bf16 v[54:57], v[82:85], v[162:165], v[54:57]
	v_mfma_f32_16x16x32_bf16 v[50:53], v[90:93], v[162:165], v[50:53]
	v_mfma_f32_16x16x32_bf16 v[34:37], v[90:93], v[170:173], v[34:37]
	v_mfma_f32_16x16x32_bf16 v[38:41], v[82:85], v[170:173], v[38:41]
	v_mfma_f32_16x16x32_bf16 v[42:45], v[66:69], v[170:173], v[42:45]
	v_mfma_f32_16x16x32_bf16 v[46:49], v[58:61], v[170:173], v[46:49]
	v_mfma_f32_16x16x32_bf16 v[30:33], v[58:61], v[178:181], v[30:33]
	v_mfma_f32_16x16x32_bf16 v[26:29], v[66:69], v[178:181], v[26:29]
	v_mfma_f32_16x16x32_bf16 v[22:25], v[82:85], v[178:181], v[22:25]
	v_mfma_f32_16x16x32_bf16 v[18:21], v[90:93], v[178:181], v[18:21]
	v_mfma_f32_16x16x32_bf16 v[2:5], v[90:93], v[202:205], v[2:5]
	v_mfma_f32_16x16x32_bf16 v[6:9], v[82:85], v[202:205], v[6:9]
	v_mfma_f32_16x16x32_bf16 v[10:13], v[66:69], v[202:205], v[10:13]
	v_mfma_f32_16x16x32_bf16 v[14:17], v[58:61], v[202:205], v[14:17]
	s_setprio 0
	s_setprio 1
	v_mfma_f32_16x16x32_bf16 v[78:81], v[62:65], v[166:169], v[78:81]
	v_mfma_f32_16x16x32_bf16 v[74:77], v[70:73], v[166:169], v[74:77]
	v_mfma_f32_16x16x32_bf16 v[54:57], v[86:89], v[166:169], v[54:57]
	v_mfma_f32_16x16x32_bf16 v[50:53], v[94:97], v[166:169], v[50:53]
	v_mfma_f32_16x16x32_bf16 v[34:37], v[94:97], v[174:177], v[34:37]
	v_mfma_f32_16x16x32_bf16 v[38:41], v[86:89], v[174:177], v[38:41]
	v_mfma_f32_16x16x32_bf16 v[42:45], v[70:73], v[174:177], v[42:45]
	v_mfma_f32_16x16x32_bf16 v[46:49], v[62:65], v[174:177], v[46:49]
	v_mfma_f32_16x16x32_bf16 v[30:33], v[62:65], v[198:201], v[30:33]
	v_mfma_f32_16x16x32_bf16 v[26:29], v[70:73], v[198:201], v[26:29]
	v_mfma_f32_16x16x32_bf16 v[22:25], v[86:89], v[198:201], v[22:25]
	v_mfma_f32_16x16x32_bf16 v[18:21], v[94:97], v[198:201], v[18:21]
	v_mfma_f32_16x16x32_bf16 v[2:5], v[94:97], v[206:209], v[2:5]
	v_mfma_f32_16x16x32_bf16 v[6:9], v[86:89], v[206:209], v[6:9]
	v_mfma_f32_16x16x32_bf16 v[10:13], v[70:73], v[206:209], v[10:13]
	v_mfma_f32_16x16x32_bf16 v[14:17], v[62:65], v[206:209], v[14:17]
	s_setprio 0
	s_barrier
	s_add_u32 s6, s6, 0x100
	s_addc_u32 s7, s7, 0
	s_add_u32 s21, s21, 0x100
	s_addc_u32 s26, s26, 0
	s_cmp_ge_u32 s46, s36
	s_mov_b32 s27, s46
	s_cbranch_scc0 .LBB0_671
	s_and_b64 vcc, exec, s[30:31]
	s_cbranch_vccz .LBB0_674
	s_barrier
